# MFMA-first schedule after each barrier: fragment reads interleaved 1:1 with MFMAs, LDS stores after reads, prefetch loads after M(Y); counted lgkmcnt
# speedup vs baseline: 1.0615x; 1.0235x over previous
.Lmya_even:
	s_waitcnt lgkmcnt(0)
	s_barrier
	v_mfma_f32_16x16x32_bf16 v[108:111], v[144:147], v[160:163], v[108:111]
	ds_read_b128 v[112:115], v206
	v_mfma_f32_16x16x32_bf16 v[104:107], v[144:147], v[164:167], v[104:107]
	ds_read_b128 v[116:119], v206 offset:2048
	v_mfma_f32_16x16x32_bf16 v[100:103], v[144:147], v[228:231], v[100:103]
	ds_read_b128 v[120:123], v206 offset:4096
	v_mfma_f32_16x16x32_bf16 v[96:99], v[144:147], v[232:235], v[96:99]
	ds_read_b128 v[124:127], v206 offset:6144
	v_mfma_f32_16x16x32_bf16 v[92:95], v[148:151], v[160:163], v[92:95]
	ds_read_b128 v[128:131], v207
	v_mfma_f32_16x16x32_bf16 v[88:91], v[148:151], v[164:167], v[88:91]
	ds_read_b128 v[132:135], v207 offset:2048
	v_mfma_f32_16x16x32_bf16 v[84:87], v[148:151], v[228:231], v[84:87]
	ds_read_b128 v[136:139], v207 offset:4096
	v_mfma_f32_16x16x32_bf16 v[80:83], v[148:151], v[232:235], v[80:83]
	ds_read_b128 v[140:143], v207 offset:6144
	s_cmp_gt_u32 s27, 12
	s_cbranch_scc0 .Lmya_ew6
	s_and_b64 vcc, exec, s[8:9]
	s_cbranch_vccnz .Lmya_ew6
	s_waitcnt vmcnt(0)
.Lmya_ew6:
	s_waitcnt vmcnt(6)
	v_mfma_f32_16x16x32_bf16 v[76:79], v[152:155], v[160:163], v[76:79]
	ds_write_b128 v204, v[0:3] offset:32768
	v_mfma_f32_16x16x32_bf16 v[72:75], v[152:155], v[164:167], v[72:75]
	ds_write_b128 v204, v[4:7] offset:40960
	v_mfma_f32_16x16x32_bf16 v[68:71], v[152:155], v[228:231], v[68:71]
	ds_write_b128 v204, v[8:11] offset:49152
	v_mfma_f32_16x16x32_bf16 v[64:67], v[152:155], v[232:235], v[64:67]
	ds_write_b128 v204, v[12:15] offset:57344
	v_mfma_f32_16x16x32_bf16 v[60:63], v[156:159], v[160:163], v[60:63]
	ds_write_b128 v210, v[32:35]
	v_mfma_f32_16x16x32_bf16 v[56:59], v[156:159], v[164:167], v[56:59]
	ds_write_b128 v210, v[44:47] offset:8192
	v_mfma_f32_16x16x32_bf16 v[52:55], v[156:159], v[228:231], v[52:55]
	v_mfma_f32_16x16x32_bf16 v[48:51], v[156:159], v[232:235], v[48:51]
	s_cmp_gt_u32 s27, 12
	s_mov_b64 s[10:11], -1
	s_cbranch_scc0 .Lmyase__227
	s_andn2_b64 vcc, exec, s[8:9]
	s_cbranch_vccnz .Lmyase__226
	global_load_dwordx4 v[4:7], v[182:183], off
	global_load_dwordx4 v[8:11], v[184:185], off
	global_load_dwordx4 v[0:3], v[178:179], off offset:128
	global_load_dwordx4 v[32:35], v[180:181], off offset:128
	global_load_dwordx4 v[12:15], v[186:187], off
	global_load_dwordx4 v[44:47], v[188:189], off

.Lmyase__229:
	s_waitcnt lgkmcnt(6)
	v_mfma_f32_16x16x32_bf16 v[108:111], v[112:115], v[128:131], v[108:111]
	ds_read_b128 v[144:147], v208
	v_mfma_f32_16x16x32_bf16 v[104:107], v[112:115], v[132:135], v[104:107]
	ds_read_b128 v[148:151], v208 offset:2048
	v_mfma_f32_16x16x32_bf16 v[100:103], v[112:115], v[136:139], v[100:103]
	ds_read_b128 v[152:155], v208 offset:4096
	v_mfma_f32_16x16x32_bf16 v[96:99], v[112:115], v[140:143], v[96:99]
	ds_read_b128 v[156:159], v208 offset:6144
	v_mfma_f32_16x16x32_bf16 v[92:95], v[116:119], v[128:131], v[92:95]
	ds_read_b128 v[160:163], v209
	v_mfma_f32_16x16x32_bf16 v[88:91], v[116:119], v[132:135], v[88:91]
	ds_read_b128 v[164:167], v209 offset:2048
	v_mfma_f32_16x16x32_bf16 v[84:87], v[116:119], v[136:139], v[84:87]
	ds_read_b128 v[228:231], v209 offset:4096
	v_mfma_f32_16x16x32_bf16 v[80:83], v[116:119], v[140:143], v[80:83]
	ds_read_b128 v[232:235], v209 offset:6144
	v_mfma_f32_16x16x32_bf16 v[76:79], v[120:123], v[128:131], v[76:79]
	v_mfma_f32_16x16x32_bf16 v[72:75], v[120:123], v[132:135], v[72:75]
	v_mfma_f32_16x16x32_bf16 v[68:71], v[120:123], v[136:139], v[68:71]
	v_mfma_f32_16x16x32_bf16 v[64:67], v[120:123], v[140:143], v[64:67]
	v_mfma_f32_16x16x32_bf16 v[60:63], v[124:127], v[128:131], v[60:63]
	v_mfma_f32_16x16x32_bf16 v[56:59], v[124:127], v[132:135], v[56:59]
	v_mfma_f32_16x16x32_bf16 v[52:55], v[124:127], v[136:139], v[52:55]
	v_mfma_f32_16x16x32_bf16 v[48:51], v[124:127], v[140:143], v[48:51]
.Lmya_odd:
	s_waitcnt lgkmcnt(0)
	s_barrier
	s_cmp_gt_u32 s27, 13
	s_cselect_b64 s[10:11], -1, 0
	s_and_b64 vcc, exec, s[10:11]
	s_cbranch_vccnz .Lmya_oddlast
	v_mfma_f32_16x16x32_bf16 v[108:111], v[144:147], v[160:163], v[108:111]
	ds_read_b128 v[112:115], v206 offset:32768
	v_mfma_f32_16x16x32_bf16 v[104:107], v[144:147], v[164:167], v[104:107]
	ds_read_b128 v[116:119], v206 offset:34816
	v_mfma_f32_16x16x32_bf16 v[100:103], v[144:147], v[228:231], v[100:103]
	ds_read_b128 v[120:123], v206 offset:36864
	v_mfma_f32_16x16x32_bf16 v[96:99], v[144:147], v[232:235], v[96:99]
	ds_read_b128 v[124:127], v206 offset:38912
	v_mfma_f32_16x16x32_bf16 v[92:95], v[148:151], v[160:163], v[92:95]
	ds_read_b128 v[128:131], v211
	v_mfma_f32_16x16x32_bf16 v[88:91], v[148:151], v[164:167], v[88:91]
	ds_read_b128 v[132:135], v211 offset:2048
	v_mfma_f32_16x16x32_bf16 v[84:87], v[148:151], v[228:231], v[84:87]
	ds_read_b128 v[136:139], v211 offset:4096
	v_mfma_f32_16x16x32_bf16 v[80:83], v[148:151], v[232:235], v[80:83]
	ds_read_b128 v[140:143], v211 offset:6144
	s_waitcnt vmcnt(6)
	v_mfma_f32_16x16x32_bf16 v[76:79], v[152:155], v[160:163], v[76:79]
	ds_write_b128 v204, v[16:19]
	v_mfma_f32_16x16x32_bf16 v[72:75], v[152:155], v[164:167], v[72:75]
	ds_write_b128 v204, v[20:23] offset:8192
	v_mfma_f32_16x16x32_bf16 v[68:71], v[152:155], v[228:231], v[68:71]
	ds_write_b128 v204, v[24:27] offset:16384
	v_mfma_f32_16x16x32_bf16 v[64:67], v[152:155], v[232:235], v[64:67]
	ds_write_b128 v204, v[36:39] offset:24576
	v_mfma_f32_16x16x32_bf16 v[60:63], v[156:159], v[160:163], v[60:63]
	ds_write_b128 v205, v[28:31]
	v_mfma_f32_16x16x32_bf16 v[56:59], v[156:159], v[164:167], v[56:59]
	ds_write_b128 v205, v[40:43] offset:8192
	v_mfma_f32_16x16x32_bf16 v[52:55], v[156:159], v[228:231], v[52:55]
	v_mfma_f32_16x16x32_bf16 v[48:51], v[156:159], v[232:235], v[48:51]
	s_cmp_gt_u32 s27, 11
	s_mov_b64 s[12:13], -1
	s_cbranch_scc0 .Lmyaso__234
	s_andn2_b64 vcc, exec, s[8:9]
	s_cbranch_vccnz .Lmyaso__233
	global_load_dwordx4 v[20:23], v[190:191], off
	global_load_dwordx4 v[24:27], v[192:193], off
	global_load_dwordx4 v[16:19], v[178:179], off
	global_load_dwordx4 v[28:31], v[180:181], off
	global_load_dwordx4 v[36:39], v[194:195], off
	global_load_dwordx4 v[40:43], v[196:197], off

.Lmya_ocont:
	s_waitcnt lgkmcnt(6)
	v_mfma_f32_16x16x32_bf16 v[108:111], v[112:115], v[128:131], v[108:111]
	ds_read_b128 v[144:147], v208 offset:32768
	v_mfma_f32_16x16x32_bf16 v[104:107], v[112:115], v[132:135], v[104:107]
	ds_read_b128 v[148:151], v208 offset:34816
	v_mfma_f32_16x16x32_bf16 v[100:103], v[112:115], v[136:139], v[100:103]
	ds_read_b128 v[152:155], v208 offset:36864
	v_mfma_f32_16x16x32_bf16 v[96:99], v[112:115], v[140:143], v[96:99]
	ds_read_b128 v[156:159], v208 offset:38912
	v_mfma_f32_16x16x32_bf16 v[92:95], v[116:119], v[128:131], v[92:95]
	ds_read_b128 v[160:163], v212
	v_mfma_f32_16x16x32_bf16 v[88:91], v[116:119], v[132:135], v[88:91]
	ds_read_b128 v[164:167], v212 offset:2048
	v_mfma_f32_16x16x32_bf16 v[84:87], v[116:119], v[136:139], v[84:87]
	ds_read_b128 v[228:231], v212 offset:4096
	v_mfma_f32_16x16x32_bf16 v[80:83], v[116:119], v[140:143], v[80:83]
	ds_read_b128 v[232:235], v212 offset:6144
	v_mfma_f32_16x16x32_bf16 v[76:79], v[120:123], v[128:131], v[76:79]
	v_mfma_f32_16x16x32_bf16 v[72:75], v[120:123], v[132:135], v[72:75]
	v_mfma_f32_16x16x32_bf16 v[68:71], v[120:123], v[136:139], v[68:71]
	v_mfma_f32_16x16x32_bf16 v[64:67], v[120:123], v[140:143], v[64:67]
	v_mfma_f32_16x16x32_bf16 v[60:63], v[124:127], v[128:131], v[60:63]
	v_mfma_f32_16x16x32_bf16 v[56:59], v[124:127], v[132:135], v[56:59]
	v_mfma_f32_16x16x32_bf16 v[52:55], v[124:127], v[136:139], v[52:55]
	v_mfma_f32_16x16x32_bf16 v[48:51], v[124:127], v[140:143], v[48:51]
	s_add_i32 s27, s27, 2
	s_add_u32 s100, s100, 0x100
	s_addc_u32 s101, s101, 0
	s_add_u32 s98, s98, 0x100
	s_addc_u32 s99, s99, 0
	s_branch .Lmya_even
.Lmya_oddlast:
	v_mfma_f32_16x16x32_bf16 v[108:111], v[144:147], v[160:163], v[108:111]
	ds_read_b128 v[112:115], v206 offset:32768
	v_mfma_f32_16x16x32_bf16 v[104:107], v[144:147], v[164:167], v[104:107]
	ds_read_b128 v[116:119], v206 offset:34816
	v_mfma_f32_16x16x32_bf16 v[100:103], v[144:147], v[228:231], v[100:103]
	ds_read_b128 v[120:123], v206 offset:36864
	v_mfma_f32_16x16x32_bf16 v[96:99], v[144:147], v[232:235], v[96:99]
	ds_read_b128 v[124:127], v206 offset:38912
	v_mfma_f32_16x16x32_bf16 v[92:95], v[148:151], v[160:163], v[92:95]
	ds_read_b128 v[128:131], v211
	v_mfma_f32_16x16x32_bf16 v[88:91], v[148:151], v[164:167], v[88:91]
	ds_read_b128 v[132:135], v211 offset:2048
	v_mfma_f32_16x16x32_bf16 v[84:87], v[148:151], v[228:231], v[84:87]
	ds_read_b128 v[136:139], v211 offset:4096
	v_mfma_f32_16x16x32_bf16 v[80:83], v[148:151], v[232:235], v[80:83]
	ds_read_b128 v[140:143], v211 offset:6144
	v_mfma_f32_16x16x32_bf16 v[76:79], v[152:155], v[160:163], v[76:79]
	v_mfma_f32_16x16x32_bf16 v[72:75], v[152:155], v[164:167], v[72:75]
	v_mfma_f32_16x16x32_bf16 v[68:71], v[152:155], v[228:231], v[68:71]
	v_mfma_f32_16x16x32_bf16 v[64:67], v[152:155], v[232:235], v[64:67]
	v_mfma_f32_16x16x32_bf16 v[60:63], v[156:159], v[160:163], v[60:63]
	v_mfma_f32_16x16x32_bf16 v[56:59], v[156:159], v[164:167], v[56:59]
	v_mfma_f32_16x16x32_bf16 v[52:55], v[156:159], v[228:231], v[52:55]
	v_mfma_f32_16x16x32_bf16 v[48:51], v[156:159], v[232:235], v[48:51]
	s_waitcnt lgkmcnt(0)
	v_mfma_f32_16x16x32_bf16 v[108:111], v[112:115], v[128:131], v[108:111]
	ds_read_b128 v[144:147], v208 offset:32768
	v_mfma_f32_16x16x32_bf16 v[104:107], v[112:115], v[132:135], v[104:107]
	ds_read_b128 v[148:151], v208 offset:34816
	v_mfma_f32_16x16x32_bf16 v[100:103], v[112:115], v[136:139], v[100:103]
	ds_read_b128 v[152:155], v208 offset:36864
	v_mfma_f32_16x16x32_bf16 v[96:99], v[112:115], v[140:143], v[96:99]
	ds_read_b128 v[156:159], v208 offset:38912
	v_mfma_f32_16x16x32_bf16 v[92:95], v[116:119], v[128:131], v[92:95]
	ds_read_b128 v[160:163], v212
	v_mfma_f32_16x16x32_bf16 v[88:91], v[116:119], v[132:135], v[88:91]
	ds_read_b128 v[164:167], v212 offset:2048
	v_mfma_f32_16x16x32_bf16 v[84:87], v[116:119], v[136:139], v[84:87]
	ds_read_b128 v[228:231], v212 offset:4096
	v_mfma_f32_16x16x32_bf16 v[80:83], v[116:119], v[140:143], v[80:83]
	ds_read_b128 v[232:235], v212 offset:6144
	v_mfma_f32_16x16x32_bf16 v[76:79], v[120:123], v[128:131], v[76:79]
	v_mfma_f32_16x16x32_bf16 v[72:75], v[120:123], v[132:135], v[72:75]
	v_mfma_f32_16x16x32_bf16 v[68:71], v[120:123], v[136:139], v[68:71]
	v_mfma_f32_16x16x32_bf16 v[64:67], v[120:123], v[140:143], v[64:67]
	v_mfma_f32_16x16x32_bf16 v[60:63], v[124:127], v[128:131], v[60:63]
	v_mfma_f32_16x16x32_bf16 v[56:59], v[124:127], v[132:135], v[56:59]
	v_mfma_f32_16x16x32_bf16 v[52:55], v[124:127], v[136:139], v[52:55]
	v_mfma_f32_16x16x32_bf16 v[48:51], v[124:127], v[140:143], v[48:51]
	s_add_i32 s27, s27, 2
	s_add_u32 s100, s100, 0x100
	s_addc_u32 s101, s101, 0
	s_add_u32 s98, s98, 0x100
	s_addc_u32 s99, s99, 0
	s_waitcnt lgkmcnt(0)
	v_mfma_f32_16x16x32_bf16 v[108:111], v[144:147], v[160:163], v[108:111]
	v_mfma_f32_16x16x32_bf16 v[104:107], v[144:147], v[164:167], v[104:107]
	v_mfma_f32_16x16x32_bf16 v[100:103], v[144:147], v[228:231], v[100:103]
	v_mfma_f32_16x16x32_bf16 v[96:99], v[144:147], v[232:235], v[96:99]
	v_mfma_f32_16x16x32_bf16 v[92:95], v[148:151], v[160:163], v[92:95]
	v_mfma_f32_16x16x32_bf16 v[88:91], v[148:151], v[164:167], v[88:91]
	v_mfma_f32_16x16x32_bf16 v[84:87], v[148:151], v[228:231], v[84:87]
	v_mfma_f32_16x16x32_bf16 v[80:83], v[148:151], v[232:235], v[80:83]
	v_mfma_f32_16x16x32_bf16 v[76:79], v[152:155], v[160:163], v[76:79]
	v_mfma_f32_16x16x32_bf16 v[72:75], v[152:155], v[164:167], v[72:75]
	v_mfma_f32_16x16x32_bf16 v[68:71], v[152:155], v[228:231], v[68:71]
	v_mfma_f32_16x16x32_bf16 v[64:67], v[152:155], v[232:235], v[64:67]
	v_mfma_f32_16x16x32_bf16 v[60:63], v[156:159], v[160:163], v[60:63]
	v_mfma_f32_16x16x32_bf16 v[56:59], v[156:159], v[164:167], v[56:59]
	v_mfma_f32_16x16x32_bf16 v[52:55], v[156:159], v[228:231], v[52:55]
	v_mfma_f32_16x16x32_bf16 v[48:51], v[156:159], v[232:235], v[48:51]
	s_and_b64 vcc, exec, s[10:11]
	s_nop 7
	s_branch .LBB0_236

.Lmyb_even:
	s_waitcnt lgkmcnt(0)
	s_barrier
	v_mfma_f32_16x16x32_bf16 v[108:111], v[144:147], v[160:163], v[108:111]
	ds_read_b128 v[112:115], v206
	v_mfma_f32_16x16x32_bf16 v[104:107], v[144:147], v[164:167], v[104:107]
	ds_read_b128 v[116:119], v206 offset:2048
	v_mfma_f32_16x16x32_bf16 v[100:103], v[144:147], v[216:219], v[100:103]
	ds_read_b128 v[120:123], v206 offset:4096
	v_mfma_f32_16x16x32_bf16 v[96:99], v[144:147], v[228:231], v[96:99]
	ds_read_b128 v[124:127], v206 offset:6144
	v_mfma_f32_16x16x32_bf16 v[92:95], v[148:151], v[160:163], v[92:95]
	ds_read_b128 v[128:131], v207
	v_mfma_f32_16x16x32_bf16 v[88:91], v[148:151], v[164:167], v[88:91]
	ds_read_b128 v[132:135], v207 offset:2048
	v_mfma_f32_16x16x32_bf16 v[84:87], v[148:151], v[216:219], v[84:87]
	ds_read_b128 v[136:139], v207 offset:4096
	v_mfma_f32_16x16x32_bf16 v[80:83], v[148:151], v[228:231], v[80:83]
	ds_read_b128 v[140:143], v207 offset:6144
	s_cmp_gt_u32 s47, 12
	s_cbranch_scc0 .Lmyb_ew6
	s_and_b64 vcc, exec, s[12:13]
	s_cbranch_vccnz .Lmyb_ew6
	s_waitcnt vmcnt(0)
.Lmyb_ew6:
	s_waitcnt vmcnt(6)
	v_mfma_f32_16x16x32_bf16 v[76:79], v[152:155], v[160:163], v[76:79]
	ds_write_b128 v204, v[0:3] offset:32768
	v_mfma_f32_16x16x32_bf16 v[72:75], v[152:155], v[164:167], v[72:75]
	ds_write_b128 v204, v[4:7] offset:40960
	v_mfma_f32_16x16x32_bf16 v[68:71], v[152:155], v[216:219], v[68:71]
	ds_write_b128 v204, v[8:11] offset:49152
	v_mfma_f32_16x16x32_bf16 v[64:67], v[152:155], v[228:231], v[64:67]
	ds_write_b128 v204, v[12:15] offset:57344
	v_mfma_f32_16x16x32_bf16 v[60:63], v[156:159], v[160:163], v[60:63]
	ds_write_b128 v210, v[16:19]
	v_mfma_f32_16x16x32_bf16 v[56:59], v[156:159], v[164:167], v[56:59]
	ds_write_b128 v210, v[24:27] offset:8192
	v_mfma_f32_16x16x32_bf16 v[52:55], v[156:159], v[216:219], v[52:55]
	v_mfma_f32_16x16x32_bf16 v[48:51], v[156:159], v[228:231], v[48:51]
	s_cmp_gt_u32 s47, 12
	s_mov_b64 s[14:15], -1
	s_cbranch_scc0 .Lmybse__637
	s_andn2_b64 vcc, exec, s[12:13]
	s_cbranch_vccnz .Lmybse__636
	global_load_dwordx4 v[4:7], v[186:187], off
	global_load_dwordx4 v[8:11], v[188:189], off
	global_load_dwordx4 v[0:3], v[182:183], off offset:128
	global_load_dwordx4 v[16:19], v[184:185], off offset:128
	global_load_dwordx4 v[12:15], v[190:191], off
	global_load_dwordx4 v[24:27], v[192:193], off

.Lmybse__639:
	s_waitcnt lgkmcnt(6)
	v_mfma_f32_16x16x32_bf16 v[108:111], v[112:115], v[128:131], v[108:111]
	ds_read_b128 v[144:147], v208
	v_mfma_f32_16x16x32_bf16 v[104:107], v[112:115], v[132:135], v[104:107]
	ds_read_b128 v[148:151], v208 offset:2048
	v_mfma_f32_16x16x32_bf16 v[100:103], v[112:115], v[136:139], v[100:103]
	ds_read_b128 v[152:155], v208 offset:4096
	v_mfma_f32_16x16x32_bf16 v[96:99], v[112:115], v[140:143], v[96:99]
	ds_read_b128 v[156:159], v208 offset:6144
	v_mfma_f32_16x16x32_bf16 v[92:95], v[116:119], v[128:131], v[92:95]
	ds_read_b128 v[160:163], v209
	v_mfma_f32_16x16x32_bf16 v[88:91], v[116:119], v[132:135], v[88:91]
	ds_read_b128 v[164:167], v209 offset:2048
	v_mfma_f32_16x16x32_bf16 v[84:87], v[116:119], v[136:139], v[84:87]
	ds_read_b128 v[216:219], v209 offset:4096
	v_mfma_f32_16x16x32_bf16 v[80:83], v[116:119], v[140:143], v[80:83]
	ds_read_b128 v[228:231], v209 offset:6144
	v_mfma_f32_16x16x32_bf16 v[76:79], v[120:123], v[128:131], v[76:79]
	v_mfma_f32_16x16x32_bf16 v[72:75], v[120:123], v[132:135], v[72:75]
	v_mfma_f32_16x16x32_bf16 v[68:71], v[120:123], v[136:139], v[68:71]
	v_mfma_f32_16x16x32_bf16 v[64:67], v[120:123], v[140:143], v[64:67]
	v_mfma_f32_16x16x32_bf16 v[60:63], v[124:127], v[128:131], v[60:63]
	v_mfma_f32_16x16x32_bf16 v[56:59], v[124:127], v[132:135], v[56:59]
	v_mfma_f32_16x16x32_bf16 v[52:55], v[124:127], v[136:139], v[52:55]
	v_mfma_f32_16x16x32_bf16 v[48:51], v[124:127], v[140:143], v[48:51]
.Lmyb_odd:
	s_waitcnt lgkmcnt(0)
	s_barrier
	s_cmp_gt_u32 s47, 13
	s_cselect_b64 s[14:15], -1, 0
	s_and_b64 vcc, exec, s[14:15]
	s_cbranch_vccnz .Lmyb_oddlast
	v_mfma_f32_16x16x32_bf16 v[108:111], v[144:147], v[160:163], v[108:111]
	ds_read_b128 v[112:115], v206 offset:32768
	v_mfma_f32_16x16x32_bf16 v[104:107], v[144:147], v[164:167], v[104:107]
	ds_read_b128 v[116:119], v206 offset:34816
	v_mfma_f32_16x16x32_bf16 v[100:103], v[144:147], v[216:219], v[100:103]
	ds_read_b128 v[120:123], v206 offset:36864
	v_mfma_f32_16x16x32_bf16 v[96:99], v[144:147], v[228:231], v[96:99]
	ds_read_b128 v[124:127], v206 offset:38912
	v_mfma_f32_16x16x32_bf16 v[92:95], v[148:151], v[160:163], v[92:95]
	ds_read_b128 v[128:131], v211
	v_mfma_f32_16x16x32_bf16 v[88:91], v[148:151], v[164:167], v[88:91]
	ds_read_b128 v[132:135], v211 offset:2048
	v_mfma_f32_16x16x32_bf16 v[84:87], v[148:151], v[216:219], v[84:87]
	ds_read_b128 v[136:139], v211 offset:4096
	v_mfma_f32_16x16x32_bf16 v[80:83], v[148:151], v[228:231], v[80:83]
	ds_read_b128 v[140:143], v211 offset:6144
	s_waitcnt vmcnt(6)
	v_mfma_f32_16x16x32_bf16 v[76:79], v[152:155], v[160:163], v[76:79]
	ds_write_b128 v204, v[36:39]
	v_mfma_f32_16x16x32_bf16 v[72:75], v[152:155], v[164:167], v[72:75]
	ds_write_b128 v204, v[44:47] offset:8192
	v_mfma_f32_16x16x32_bf16 v[68:71], v[152:155], v[216:219], v[68:71]
	ds_write_b128 v204, v[32:35] offset:16384
	v_mfma_f32_16x16x32_bf16 v[64:67], v[152:155], v[228:231], v[64:67]
	ds_write_b128 v204, v[40:43] offset:24576
	v_mfma_f32_16x16x32_bf16 v[60:63], v[156:159], v[160:163], v[60:63]
	ds_write_b128 v205, v[20:23]
	v_mfma_f32_16x16x32_bf16 v[56:59], v[156:159], v[164:167], v[56:59]
	ds_write_b128 v205, v[28:31] offset:8192
	v_mfma_f32_16x16x32_bf16 v[52:55], v[156:159], v[216:219], v[52:55]
	v_mfma_f32_16x16x32_bf16 v[48:51], v[156:159], v[228:231], v[48:51]
	s_cmp_gt_u32 s47, 11
	s_mov_b64 s[16:17], -1
	s_cbranch_scc0 .Lmybso__644
	s_andn2_b64 vcc, exec, s[12:13]
	s_cbranch_vccnz .Lmybso__643
	global_load_dwordx4 v[44:47], v[194:195], off
	global_load_dwordx4 v[32:35], v[196:197], off
	global_load_dwordx4 v[36:39], v[182:183], off
	global_load_dwordx4 v[20:23], v[184:185], off
	global_load_dwordx4 v[40:43], v[198:199], off
	global_load_dwordx4 v[28:31], v[200:201], off

.Lmyb_ocont:
	s_waitcnt lgkmcnt(6)
	v_mfma_f32_16x16x32_bf16 v[108:111], v[112:115], v[128:131], v[108:111]
	ds_read_b128 v[144:147], v208 offset:32768
	v_mfma_f32_16x16x32_bf16 v[104:107], v[112:115], v[132:135], v[104:107]
	ds_read_b128 v[148:151], v208 offset:34816
	v_mfma_f32_16x16x32_bf16 v[100:103], v[112:115], v[136:139], v[100:103]
	ds_read_b128 v[152:155], v208 offset:36864
	v_mfma_f32_16x16x32_bf16 v[96:99], v[112:115], v[140:143], v[96:99]
	ds_read_b128 v[156:159], v208 offset:38912
	v_mfma_f32_16x16x32_bf16 v[92:95], v[116:119], v[128:131], v[92:95]
	ds_read_b128 v[160:163], v212
	v_mfma_f32_16x16x32_bf16 v[88:91], v[116:119], v[132:135], v[88:91]
	ds_read_b128 v[164:167], v212 offset:2048
	v_mfma_f32_16x16x32_bf16 v[84:87], v[116:119], v[136:139], v[84:87]
	ds_read_b128 v[216:219], v212 offset:4096
	v_mfma_f32_16x16x32_bf16 v[80:83], v[116:119], v[140:143], v[80:83]
	ds_read_b128 v[228:231], v212 offset:6144
	v_mfma_f32_16x16x32_bf16 v[76:79], v[120:123], v[128:131], v[76:79]
	v_mfma_f32_16x16x32_bf16 v[72:75], v[120:123], v[132:135], v[72:75]
	v_mfma_f32_16x16x32_bf16 v[68:71], v[120:123], v[136:139], v[68:71]
	v_mfma_f32_16x16x32_bf16 v[64:67], v[120:123], v[140:143], v[64:67]
	v_mfma_f32_16x16x32_bf16 v[60:63], v[124:127], v[128:131], v[60:63]
	v_mfma_f32_16x16x32_bf16 v[56:59], v[124:127], v[132:135], v[56:59]
	v_mfma_f32_16x16x32_bf16 v[52:55], v[124:127], v[136:139], v[52:55]
	v_mfma_f32_16x16x32_bf16 v[48:51], v[124:127], v[140:143], v[48:51]
	s_add_i32 s47, s47, 2
	s_add_u32 s100, s100, 0x100
	s_addc_u32 s101, s101, 0
	s_add_u32 s98, s98, 0x100
	s_addc_u32 s99, s99, 0
	s_branch .Lmyb_even
.Lmyb_oddlast:
	v_mfma_f32_16x16x32_bf16 v[108:111], v[144:147], v[160:163], v[108:111]
	ds_read_b128 v[112:115], v206 offset:32768
	v_mfma_f32_16x16x32_bf16 v[104:107], v[144:147], v[164:167], v[104:107]
	ds_read_b128 v[116:119], v206 offset:34816
	v_mfma_f32_16x16x32_bf16 v[100:103], v[144:147], v[216:219], v[100:103]
	ds_read_b128 v[120:123], v206 offset:36864
	v_mfma_f32_16x16x32_bf16 v[96:99], v[144:147], v[228:231], v[96:99]
	ds_read_b128 v[124:127], v206 offset:38912
	v_mfma_f32_16x16x32_bf16 v[92:95], v[148:151], v[160:163], v[92:95]
	ds_read_b128 v[128:131], v211
	v_mfma_f32_16x16x32_bf16 v[88:91], v[148:151], v[164:167], v[88:91]
	ds_read_b128 v[132:135], v211 offset:2048
	v_mfma_f32_16x16x32_bf16 v[84:87], v[148:151], v[216:219], v[84:87]
	ds_read_b128 v[136:139], v211 offset:4096
	v_mfma_f32_16x16x32_bf16 v[80:83], v[148:151], v[228:231], v[80:83]
	ds_read_b128 v[140:143], v211 offset:6144
	v_mfma_f32_16x16x32_bf16 v[76:79], v[152:155], v[160:163], v[76:79]
	v_mfma_f32_16x16x32_bf16 v[72:75], v[152:155], v[164:167], v[72:75]
	v_mfma_f32_16x16x32_bf16 v[68:71], v[152:155], v[216:219], v[68:71]
	v_mfma_f32_16x16x32_bf16 v[64:67], v[152:155], v[228:231], v[64:67]
	v_mfma_f32_16x16x32_bf16 v[60:63], v[156:159], v[160:163], v[60:63]
	v_mfma_f32_16x16x32_bf16 v[56:59], v[156:159], v[164:167], v[56:59]
	v_mfma_f32_16x16x32_bf16 v[52:55], v[156:159], v[216:219], v[52:55]
	v_mfma_f32_16x16x32_bf16 v[48:51], v[156:159], v[228:231], v[48:51]
	s_waitcnt lgkmcnt(0)
	v_mfma_f32_16x16x32_bf16 v[108:111], v[112:115], v[128:131], v[108:111]
	ds_read_b128 v[144:147], v208 offset:32768
	v_mfma_f32_16x16x32_bf16 v[104:107], v[112:115], v[132:135], v[104:107]
	ds_read_b128 v[148:151], v208 offset:34816
	v_mfma_f32_16x16x32_bf16 v[100:103], v[112:115], v[136:139], v[100:103]
	ds_read_b128 v[152:155], v208 offset:36864
	v_mfma_f32_16x16x32_bf16 v[96:99], v[112:115], v[140:143], v[96:99]
	ds_read_b128 v[156:159], v208 offset:38912
	v_mfma_f32_16x16x32_bf16 v[92:95], v[116:119], v[128:131], v[92:95]
	ds_read_b128 v[160:163], v212
	v_mfma_f32_16x16x32_bf16 v[88:91], v[116:119], v[132:135], v[88:91]
	ds_read_b128 v[164:167], v212 offset:2048
	v_mfma_f32_16x16x32_bf16 v[84:87], v[116:119], v[136:139], v[84:87]
	ds_read_b128 v[216:219], v212 offset:4096
	v_mfma_f32_16x16x32_bf16 v[80:83], v[116:119], v[140:143], v[80:83]
	ds_read_b128 v[228:231], v212 offset:6144
	v_mfma_f32_16x16x32_bf16 v[76:79], v[120:123], v[128:131], v[76:79]
	v_mfma_f32_16x16x32_bf16 v[72:75], v[120:123], v[132:135], v[72:75]
	v_mfma_f32_16x16x32_bf16 v[68:71], v[120:123], v[136:139], v[68:71]
	v_mfma_f32_16x16x32_bf16 v[64:67], v[120:123], v[140:143], v[64:67]
	v_mfma_f32_16x16x32_bf16 v[60:63], v[124:127], v[128:131], v[60:63]
	v_mfma_f32_16x16x32_bf16 v[56:59], v[124:127], v[132:135], v[56:59]
	v_mfma_f32_16x16x32_bf16 v[52:55], v[124:127], v[136:139], v[52:55]
	v_mfma_f32_16x16x32_bf16 v[48:51], v[124:127], v[140:143], v[48:51]
	s_add_i32 s47, s47, 2
	s_add_u32 s100, s100, 0x100
	s_addc_u32 s101, s101, 0
	s_add_u32 s98, s98, 0x100
	s_addc_u32 s99, s99, 0
	s_waitcnt lgkmcnt(0)
	v_mfma_f32_16x16x32_bf16 v[108:111], v[144:147], v[160:163], v[108:111]
	v_mfma_f32_16x16x32_bf16 v[104:107], v[144:147], v[164:167], v[104:107]
	v_mfma_f32_16x16x32_bf16 v[100:103], v[144:147], v[216:219], v[100:103]
	v_mfma_f32_16x16x32_bf16 v[96:99], v[144:147], v[228:231], v[96:99]
	v_mfma_f32_16x16x32_bf16 v[92:95], v[148:151], v[160:163], v[92:95]
	v_mfma_f32_16x16x32_bf16 v[88:91], v[148:151], v[164:167], v[88:91]
	v_mfma_f32_16x16x32_bf16 v[84:87], v[148:151], v[216:219], v[84:87]
	v_mfma_f32_16x16x32_bf16 v[80:83], v[148:151], v[228:231], v[80:83]
	v_mfma_f32_16x16x32_bf16 v[76:79], v[152:155], v[160:163], v[76:79]
	v_mfma_f32_16x16x32_bf16 v[72:75], v[152:155], v[164:167], v[72:75]
	v_mfma_f32_16x16x32_bf16 v[68:71], v[152:155], v[216:219], v[68:71]
	v_mfma_f32_16x16x32_bf16 v[64:67], v[152:155], v[228:231], v[64:67]
	v_mfma_f32_16x16x32_bf16 v[60:63], v[156:159], v[160:163], v[60:63]
	v_mfma_f32_16x16x32_bf16 v[56:59], v[156:159], v[164:167], v[56:59]
	v_mfma_f32_16x16x32_bf16 v[52:55], v[156:159], v[216:219], v[52:55]
	v_mfma_f32_16x16x32_bf16 v[48:51], v[156:159], v[228:231], v[48:51]
	s_and_b64 vcc, exec, s[14:15]
	s_nop 7
	s_branch .LBB0_646

.Lmyc_even:
	s_waitcnt lgkmcnt(0)
	s_barrier
	v_mfma_f32_16x16x32_bf16 v[108:111], v[160:163], v[144:147], v[108:111]
	ds_read_b128 v[112:115], v206
	v_mfma_f32_16x16x32_bf16 v[104:107], v[164:167], v[144:147], v[104:107]
	ds_read_b128 v[116:119], v206 offset:2048
	v_mfma_f32_16x16x32_bf16 v[100:103], v[216:219], v[144:147], v[100:103]
	ds_read_b128 v[120:123], v206 offset:4096
	v_mfma_f32_16x16x32_bf16 v[96:99], v[228:231], v[144:147], v[96:99]
	ds_read_b128 v[124:127], v206 offset:6144
	v_mfma_f32_16x16x32_bf16 v[92:95], v[160:163], v[148:151], v[92:95]
	ds_read_b128 v[128:131], v207
	v_mfma_f32_16x16x32_bf16 v[88:91], v[164:167], v[148:151], v[88:91]
	ds_read_b128 v[132:135], v207 offset:2048
	v_mfma_f32_16x16x32_bf16 v[84:87], v[216:219], v[148:151], v[84:87]
	ds_read_b128 v[136:139], v207 offset:4096
	v_mfma_f32_16x16x32_bf16 v[80:83], v[228:231], v[148:151], v[80:83]
	ds_read_b128 v[140:143], v207 offset:6144
	s_cmp_gt_u32 s38, 12
	s_cbranch_scc0 .Lmyc_ew6
	s_and_b64 vcc, exec, s[16:17]
	s_cbranch_vccnz .Lmyc_ew6
	s_waitcnt vmcnt(0)
.Lmyc_ew6:
	s_waitcnt vmcnt(6)
	v_mfma_f32_16x16x32_bf16 v[76:79], v[160:163], v[152:155], v[76:79]
	ds_write_b128 v204, v[0:3] offset:32768
	v_mfma_f32_16x16x32_bf16 v[72:75], v[164:167], v[152:155], v[72:75]
	ds_write_b128 v204, v[4:7] offset:40960
	v_mfma_f32_16x16x32_bf16 v[68:71], v[216:219], v[152:155], v[68:71]
	ds_write_b128 v204, v[8:11] offset:49152
	v_mfma_f32_16x16x32_bf16 v[64:67], v[228:231], v[152:155], v[64:67]
	ds_write_b128 v204, v[16:19] offset:57344
	v_mfma_f32_16x16x32_bf16 v[60:63], v[160:163], v[156:159], v[60:63]
	ds_write_b128 v210, v[28:31]
	v_mfma_f32_16x16x32_bf16 v[56:59], v[164:167], v[156:159], v[56:59]
	ds_write_b128 v210, v[36:39] offset:8192
	v_mfma_f32_16x16x32_bf16 v[52:55], v[216:219], v[156:159], v[52:55]
	v_mfma_f32_16x16x32_bf16 v[48:51], v[228:231], v[156:159], v[48:51]
	s_cmp_gt_u32 s38, 12
	s_mov_b64 s[18:19], -1
	s_cbranch_scc0 .Lmycse__778
	s_andn2_b64 vcc, exec, s[16:17]
	s_cbranch_vccnz .Lmycse__777
	global_load_dwordx4 v[4:7], v[186:187], off
	global_load_dwordx4 v[8:11], v[188:189], off
	global_load_dwordx4 v[0:3], v[182:183], off offset:128
	global_load_dwordx4 v[28:31], v[184:185], off offset:128
	global_load_dwordx4 v[16:19], v[190:191], off
	global_load_dwordx4 v[36:39], v[192:193], off

.Lmycse__780:
	s_waitcnt lgkmcnt(6)
	v_mfma_f32_16x16x32_bf16 v[108:111], v[128:131], v[112:115], v[108:111]
	ds_read_b128 v[144:147], v208
	v_mfma_f32_16x16x32_bf16 v[104:107], v[132:135], v[112:115], v[104:107]
	ds_read_b128 v[148:151], v208 offset:2048
	v_mfma_f32_16x16x32_bf16 v[100:103], v[136:139], v[112:115], v[100:103]
	ds_read_b128 v[152:155], v208 offset:4096
	v_mfma_f32_16x16x32_bf16 v[96:99], v[140:143], v[112:115], v[96:99]
	ds_read_b128 v[156:159], v208 offset:6144
	v_mfma_f32_16x16x32_bf16 v[92:95], v[128:131], v[116:119], v[92:95]
	ds_read_b128 v[160:163], v209
	v_mfma_f32_16x16x32_bf16 v[88:91], v[132:135], v[116:119], v[88:91]
	ds_read_b128 v[164:167], v209 offset:2048
	v_mfma_f32_16x16x32_bf16 v[84:87], v[136:139], v[116:119], v[84:87]
	ds_read_b128 v[216:219], v209 offset:4096
	v_mfma_f32_16x16x32_bf16 v[80:83], v[140:143], v[116:119], v[80:83]
	ds_read_b128 v[228:231], v209 offset:6144
	v_mfma_f32_16x16x32_bf16 v[76:79], v[128:131], v[120:123], v[76:79]
	v_mfma_f32_16x16x32_bf16 v[72:75], v[132:135], v[120:123], v[72:75]
	v_mfma_f32_16x16x32_bf16 v[68:71], v[136:139], v[120:123], v[68:71]
	v_mfma_f32_16x16x32_bf16 v[64:67], v[140:143], v[120:123], v[64:67]
	v_mfma_f32_16x16x32_bf16 v[60:63], v[128:131], v[124:127], v[60:63]
	v_mfma_f32_16x16x32_bf16 v[56:59], v[132:135], v[124:127], v[56:59]
	v_mfma_f32_16x16x32_bf16 v[52:55], v[136:139], v[124:127], v[52:55]
	v_mfma_f32_16x16x32_bf16 v[48:51], v[140:143], v[124:127], v[48:51]
.Lmyc_odd:
	s_waitcnt lgkmcnt(0)
	s_barrier
	s_cmp_gt_u32 s38, 13
	s_cselect_b64 s[18:19], -1, 0
	s_and_b64 vcc, exec, s[18:19]
	s_cbranch_vccnz .Lmyc_oddlast
	v_mfma_f32_16x16x32_bf16 v[108:111], v[160:163], v[144:147], v[108:111]
	ds_read_b128 v[112:115], v206 offset:32768
	v_mfma_f32_16x16x32_bf16 v[104:107], v[164:167], v[144:147], v[104:107]
	ds_read_b128 v[116:119], v206 offset:34816
	v_mfma_f32_16x16x32_bf16 v[100:103], v[216:219], v[144:147], v[100:103]
	ds_read_b128 v[120:123], v206 offset:36864
	v_mfma_f32_16x16x32_bf16 v[96:99], v[228:231], v[144:147], v[96:99]
	ds_read_b128 v[124:127], v206 offset:38912
	v_mfma_f32_16x16x32_bf16 v[92:95], v[160:163], v[148:151], v[92:95]
	ds_read_b128 v[128:131], v211
	v_mfma_f32_16x16x32_bf16 v[88:91], v[164:167], v[148:151], v[88:91]
	ds_read_b128 v[132:135], v211 offset:2048
	v_mfma_f32_16x16x32_bf16 v[84:87], v[216:219], v[148:151], v[84:87]
	ds_read_b128 v[136:139], v211 offset:4096
	v_mfma_f32_16x16x32_bf16 v[80:83], v[228:231], v[148:151], v[80:83]
	ds_read_b128 v[140:143], v211 offset:6144
	s_waitcnt vmcnt(6)
	v_mfma_f32_16x16x32_bf16 v[76:79], v[160:163], v[152:155], v[76:79]
	ds_write_b128 v204, v[12:15]
	v_mfma_f32_16x16x32_bf16 v[72:75], v[164:167], v[152:155], v[72:75]
	ds_write_b128 v204, v[20:23] offset:8192
	v_mfma_f32_16x16x32_bf16 v[68:71], v[216:219], v[152:155], v[68:71]
	ds_write_b128 v204, v[32:35] offset:16384
	v_mfma_f32_16x16x32_bf16 v[64:67], v[228:231], v[152:155], v[64:67]
	ds_write_b128 v204, v[24:27] offset:24576
	v_mfma_f32_16x16x32_bf16 v[60:63], v[160:163], v[156:159], v[60:63]
	ds_write_b128 v205, v[44:47]
	v_mfma_f32_16x16x32_bf16 v[56:59], v[164:167], v[156:159], v[56:59]
	ds_write_b128 v205, v[40:43] offset:8192
	v_mfma_f32_16x16x32_bf16 v[52:55], v[216:219], v[156:159], v[52:55]
	v_mfma_f32_16x16x32_bf16 v[48:51], v[228:231], v[156:159], v[48:51]
	s_cmp_gt_u32 s38, 11
	s_mov_b64 s[20:21], -1
	s_cbranch_scc0 .Lmycso__785
	s_andn2_b64 vcc, exec, s[16:17]
	s_cbranch_vccnz .Lmycso__784
	global_load_dwordx4 v[20:23], v[194:195], off
	global_load_dwordx4 v[32:35], v[196:197], off
	global_load_dwordx4 v[12:15], v[182:183], off
	global_load_dwordx4 v[44:47], v[184:185], off
	global_load_dwordx4 v[24:27], v[198:199], off
	global_load_dwordx4 v[40:43], v[200:201], off

.Lmyc_ocont:
	s_waitcnt lgkmcnt(6)
	v_mfma_f32_16x16x32_bf16 v[108:111], v[128:131], v[112:115], v[108:111]
	ds_read_b128 v[144:147], v208 offset:32768
	v_mfma_f32_16x16x32_bf16 v[104:107], v[132:135], v[112:115], v[104:107]
	ds_read_b128 v[148:151], v208 offset:34816
	v_mfma_f32_16x16x32_bf16 v[100:103], v[136:139], v[112:115], v[100:103]
	ds_read_b128 v[152:155], v208 offset:36864
	v_mfma_f32_16x16x32_bf16 v[96:99], v[140:143], v[112:115], v[96:99]
	ds_read_b128 v[156:159], v208 offset:38912
	v_mfma_f32_16x16x32_bf16 v[92:95], v[128:131], v[116:119], v[92:95]
	ds_read_b128 v[160:163], v212
	v_mfma_f32_16x16x32_bf16 v[88:91], v[132:135], v[116:119], v[88:91]
	ds_read_b128 v[164:167], v212 offset:2048
	v_mfma_f32_16x16x32_bf16 v[84:87], v[136:139], v[116:119], v[84:87]
	ds_read_b128 v[216:219], v212 offset:4096
	v_mfma_f32_16x16x32_bf16 v[80:83], v[140:143], v[116:119], v[80:83]
	ds_read_b128 v[228:231], v212 offset:6144
	v_mfma_f32_16x16x32_bf16 v[76:79], v[128:131], v[120:123], v[76:79]
	v_mfma_f32_16x16x32_bf16 v[72:75], v[132:135], v[120:123], v[72:75]
	v_mfma_f32_16x16x32_bf16 v[68:71], v[136:139], v[120:123], v[68:71]
	v_mfma_f32_16x16x32_bf16 v[64:67], v[140:143], v[120:123], v[64:67]
	v_mfma_f32_16x16x32_bf16 v[60:63], v[128:131], v[124:127], v[60:63]
	v_mfma_f32_16x16x32_bf16 v[56:59], v[132:135], v[124:127], v[56:59]
	v_mfma_f32_16x16x32_bf16 v[52:55], v[136:139], v[124:127], v[52:55]
	v_mfma_f32_16x16x32_bf16 v[48:51], v[140:143], v[124:127], v[48:51]
	s_add_i32 s38, s38, 2
	s_add_u32 s100, s100, 0x100
	s_addc_u32 s101, s101, 0
	s_add_u32 s98, s98, 0x100
	s_addc_u32 s99, s99, 0
	s_branch .Lmyc_even
.Lmyc_oddlast:
	v_mfma_f32_16x16x32_bf16 v[108:111], v[160:163], v[144:147], v[108:111]
	ds_read_b128 v[112:115], v206 offset:32768
	v_mfma_f32_16x16x32_bf16 v[104:107], v[164:167], v[144:147], v[104:107]
	ds_read_b128 v[116:119], v206 offset:34816
	v_mfma_f32_16x16x32_bf16 v[100:103], v[216:219], v[144:147], v[100:103]
	ds_read_b128 v[120:123], v206 offset:36864
	v_mfma_f32_16x16x32_bf16 v[96:99], v[228:231], v[144:147], v[96:99]
	ds_read_b128 v[124:127], v206 offset:38912
	v_mfma_f32_16x16x32_bf16 v[92:95], v[160:163], v[148:151], v[92:95]
	ds_read_b128 v[128:131], v211
	v_mfma_f32_16x16x32_bf16 v[88:91], v[164:167], v[148:151], v[88:91]
	ds_read_b128 v[132:135], v211 offset:2048
	v_mfma_f32_16x16x32_bf16 v[84:87], v[216:219], v[148:151], v[84:87]
	ds_read_b128 v[136:139], v211 offset:4096
	v_mfma_f32_16x16x32_bf16 v[80:83], v[228:231], v[148:151], v[80:83]
	ds_read_b128 v[140:143], v211 offset:6144
	v_mfma_f32_16x16x32_bf16 v[76:79], v[160:163], v[152:155], v[76:79]
	v_mfma_f32_16x16x32_bf16 v[72:75], v[164:167], v[152:155], v[72:75]
	v_mfma_f32_16x16x32_bf16 v[68:71], v[216:219], v[152:155], v[68:71]
	v_mfma_f32_16x16x32_bf16 v[64:67], v[228:231], v[152:155], v[64:67]
	v_mfma_f32_16x16x32_bf16 v[60:63], v[160:163], v[156:159], v[60:63]
	v_mfma_f32_16x16x32_bf16 v[56:59], v[164:167], v[156:159], v[56:59]
	v_mfma_f32_16x16x32_bf16 v[52:55], v[216:219], v[156:159], v[52:55]
	v_mfma_f32_16x16x32_bf16 v[48:51], v[228:231], v[156:159], v[48:51]
	s_waitcnt lgkmcnt(0)
	v_mfma_f32_16x16x32_bf16 v[108:111], v[128:131], v[112:115], v[108:111]
	ds_read_b128 v[144:147], v208 offset:32768
	v_mfma_f32_16x16x32_bf16 v[104:107], v[132:135], v[112:115], v[104:107]
	ds_read_b128 v[148:151], v208 offset:34816
	v_mfma_f32_16x16x32_bf16 v[100:103], v[136:139], v[112:115], v[100:103]
	ds_read_b128 v[152:155], v208 offset:36864
	v_mfma_f32_16x16x32_bf16 v[96:99], v[140:143], v[112:115], v[96:99]
	ds_read_b128 v[156:159], v208 offset:38912
	v_mfma_f32_16x16x32_bf16 v[92:95], v[128:131], v[116:119], v[92:95]
	ds_read_b128 v[160:163], v212
	v_mfma_f32_16x16x32_bf16 v[88:91], v[132:135], v[116:119], v[88:91]
	ds_read_b128 v[164:167], v212 offset:2048
	v_mfma_f32_16x16x32_bf16 v[84:87], v[136:139], v[116:119], v[84:87]
	ds_read_b128 v[216:219], v212 offset:4096
	v_mfma_f32_16x16x32_bf16 v[80:83], v[140:143], v[116:119], v[80:83]
	ds_read_b128 v[228:231], v212 offset:6144
	v_mfma_f32_16x16x32_bf16 v[76:79], v[128:131], v[120:123], v[76:79]
	v_mfma_f32_16x16x32_bf16 v[72:75], v[132:135], v[120:123], v[72:75]
	v_mfma_f32_16x16x32_bf16 v[68:71], v[136:139], v[120:123], v[68:71]
	v_mfma_f32_16x16x32_bf16 v[64:67], v[140:143], v[120:123], v[64:67]
	v_mfma_f32_16x16x32_bf16 v[60:63], v[128:131], v[124:127], v[60:63]
	v_mfma_f32_16x16x32_bf16 v[56:59], v[132:135], v[124:127], v[56:59]
	v_mfma_f32_16x16x32_bf16 v[52:55], v[136:139], v[124:127], v[52:55]
	v_mfma_f32_16x16x32_bf16 v[48:51], v[140:143], v[124:127], v[48:51]
	s_add_i32 s38, s38, 2
	s_add_u32 s100, s100, 0x100
	s_addc_u32 s101, s101, 0
	s_add_u32 s98, s98, 0x100
	s_addc_u32 s99, s99, 0
	s_waitcnt lgkmcnt(0)
	v_mfma_f32_16x16x32_bf16 v[108:111], v[160:163], v[144:147], v[108:111]
	v_mfma_f32_16x16x32_bf16 v[104:107], v[164:167], v[144:147], v[104:107]
	v_mfma_f32_16x16x32_bf16 v[100:103], v[216:219], v[144:147], v[100:103]
	v_mfma_f32_16x16x32_bf16 v[96:99], v[228:231], v[144:147], v[96:99]
	v_mfma_f32_16x16x32_bf16 v[92:95], v[160:163], v[148:151], v[92:95]
	v_mfma_f32_16x16x32_bf16 v[88:91], v[164:167], v[148:151], v[88:91]
	v_mfma_f32_16x16x32_bf16 v[84:87], v[216:219], v[148:151], v[84:87]
	v_mfma_f32_16x16x32_bf16 v[80:83], v[228:231], v[148:151], v[80:83]
	v_mfma_f32_16x16x32_bf16 v[76:79], v[160:163], v[152:155], v[76:79]
	v_mfma_f32_16x16x32_bf16 v[72:75], v[164:167], v[152:155], v[72:75]
	v_mfma_f32_16x16x32_bf16 v[68:71], v[216:219], v[152:155], v[68:71]
	v_mfma_f32_16x16x32_bf16 v[64:67], v[228:231], v[152:155], v[64:67]
	v_mfma_f32_16x16x32_bf16 v[60:63], v[160:163], v[156:159], v[60:63]
	v_mfma_f32_16x16x32_bf16 v[56:59], v[164:167], v[156:159], v[56:59]
	v_mfma_f32_16x16x32_bf16 v[52:55], v[216:219], v[156:159], v[52:55]
	v_mfma_f32_16x16x32_bf16 v[48:51], v[228:231], v[156:159], v[48:51]
	s_and_b64 vcc, exec, s[18:19]
	s_nop 7
	s_branch .LBB0_769

.Lmyd_even:
	s_waitcnt lgkmcnt(0)
	s_barrier
	v_mfma_f32_16x16x32_bf16 v[110:113], v[146:149], v[162:165], v[110:113]
	ds_read_b128 v[114:117], v224
	v_mfma_f32_16x16x32_bf16 v[106:109], v[146:149], v[234:237], v[106:109]
	ds_read_b128 v[118:121], v224 offset:2048
	v_mfma_f32_16x16x32_bf16 v[78:81], v[146:149], v[238:241], v[78:81]
	ds_read_b128 v[122:125], v224 offset:4096
	v_mfma_f32_16x16x32_bf16 v[74:77], v[146:149], v[242:245], v[74:77]
	ds_read_b128 v[126:129], v224 offset:6144
	v_mfma_f32_16x16x32_bf16 v[102:105], v[150:153], v[162:165], v[102:105]
	ds_read_b128 v[130:133], v225
	v_mfma_f32_16x16x32_bf16 v[98:101], v[150:153], v[234:237], v[98:101]
	ds_read_b128 v[134:137], v225 offset:2048
	v_mfma_f32_16x16x32_bf16 v[70:73], v[150:153], v[238:241], v[70:73]
	ds_read_b128 v[138:141], v225 offset:4096
	v_mfma_f32_16x16x32_bf16 v[66:69], v[150:153], v[242:245], v[66:69]
	ds_read_b128 v[142:145], v225 offset:6144
	s_cmp_gt_u32 s13, 12
	s_cbranch_scc0 .Lmyd_ew6
	s_and_b64 vcc, exec, s[0:1]
	s_cbranch_vccnz .Lmyd_ew6
	s_waitcnt vmcnt(0)
.Lmyd_ew6:
	s_waitcnt vmcnt(6)
	v_mfma_f32_16x16x32_bf16 v[94:97], v[154:157], v[162:165], v[94:97]
	ds_write_b128 v222, v[2:5] offset:32768
	v_mfma_f32_16x16x32_bf16 v[90:93], v[154:157], v[234:237], v[90:93]
	ds_write_b128 v222, v[6:9] offset:40960
	v_mfma_f32_16x16x32_bf16 v[62:65], v[154:157], v[238:241], v[62:65]
	ds_write_b128 v222, v[10:13] offset:49152
	v_mfma_f32_16x16x32_bf16 v[58:61], v[154:157], v[242:245], v[58:61]
	ds_write_b128 v222, v[14:17] offset:57344
	v_mfma_f32_16x16x32_bf16 v[86:89], v[158:161], v[162:165], v[86:89]
	ds_write_b128 v228, v[18:21]
	v_mfma_f32_16x16x32_bf16 v[82:85], v[158:161], v[234:237], v[82:85]
	ds_write_b128 v228, v[26:29] offset:8192
	v_mfma_f32_16x16x32_bf16 v[54:57], v[158:161], v[238:241], v[54:57]
	v_mfma_f32_16x16x32_bf16 v[50:53], v[158:161], v[242:245], v[50:53]
	s_cmp_gt_u32 s13, 12
	s_mov_b64 s[2:3], -1
	s_cbranch_scc0 .Lmydse__1044
	s_andn2_b64 vcc, exec, s[0:1]
	s_cbranch_vccnz .Lmydse__1043
	global_load_dwordx4 v[6:9], v[184:185], off
	global_load_dwordx4 v[10:13], v[186:187], off
	global_load_dwordx4 v[2:5], v[180:181], off offset:128
	global_load_dwordx4 v[18:21], v[182:183], off offset:128
	global_load_dwordx4 v[14:17], v[188:189], off
	global_load_dwordx4 v[26:29], v[190:191], off

.Lmydse__1046:
	s_waitcnt lgkmcnt(6)
	v_mfma_f32_16x16x32_bf16 v[110:113], v[114:117], v[130:133], v[110:113]
	ds_read_b128 v[146:149], v226
	v_mfma_f32_16x16x32_bf16 v[106:109], v[114:117], v[134:137], v[106:109]
	ds_read_b128 v[150:153], v226 offset:2048
	v_mfma_f32_16x16x32_bf16 v[78:81], v[114:117], v[138:141], v[78:81]
	ds_read_b128 v[154:157], v226 offset:4096
	v_mfma_f32_16x16x32_bf16 v[74:77], v[114:117], v[142:145], v[74:77]
	ds_read_b128 v[158:161], v226 offset:6144
	v_mfma_f32_16x16x32_bf16 v[102:105], v[118:121], v[130:133], v[102:105]
	ds_read_b128 v[162:165], v227
	v_mfma_f32_16x16x32_bf16 v[98:101], v[118:121], v[134:137], v[98:101]
	ds_read_b128 v[234:237], v227 offset:2048
	v_mfma_f32_16x16x32_bf16 v[70:73], v[118:121], v[138:141], v[70:73]
	ds_read_b128 v[238:241], v227 offset:4096
	v_mfma_f32_16x16x32_bf16 v[66:69], v[118:121], v[142:145], v[66:69]
	ds_read_b128 v[242:245], v227 offset:6144
	v_mfma_f32_16x16x32_bf16 v[94:97], v[122:125], v[130:133], v[94:97]
	v_mfma_f32_16x16x32_bf16 v[90:93], v[122:125], v[134:137], v[90:93]
	v_mfma_f32_16x16x32_bf16 v[62:65], v[122:125], v[138:141], v[62:65]
	v_mfma_f32_16x16x32_bf16 v[58:61], v[122:125], v[142:145], v[58:61]
	v_mfma_f32_16x16x32_bf16 v[86:89], v[126:129], v[130:133], v[86:89]
	v_mfma_f32_16x16x32_bf16 v[82:85], v[126:129], v[134:137], v[82:85]
	v_mfma_f32_16x16x32_bf16 v[54:57], v[126:129], v[138:141], v[54:57]
	v_mfma_f32_16x16x32_bf16 v[50:53], v[126:129], v[142:145], v[50:53]
.Lmyd_odd:
	s_waitcnt lgkmcnt(0)
	s_barrier
	s_cmp_gt_u32 s13, 13
	s_cselect_b64 s[2:3], -1, 0
	s_and_b64 vcc, exec, s[2:3]
	s_cbranch_vccnz .Lmyd_oddlast
	v_mfma_f32_16x16x32_bf16 v[110:113], v[146:149], v[162:165], v[110:113]
	ds_read_b128 v[114:117], v224 offset:32768
	v_mfma_f32_16x16x32_bf16 v[106:109], v[146:149], v[234:237], v[106:109]
	ds_read_b128 v[118:121], v224 offset:34816
	v_mfma_f32_16x16x32_bf16 v[78:81], v[146:149], v[238:241], v[78:81]
	ds_read_b128 v[122:125], v224 offset:36864
	v_mfma_f32_16x16x32_bf16 v[74:77], v[146:149], v[242:245], v[74:77]
	ds_read_b128 v[126:129], v224 offset:38912
	v_mfma_f32_16x16x32_bf16 v[102:105], v[150:153], v[162:165], v[102:105]
	ds_read_b128 v[130:133], v229
	v_mfma_f32_16x16x32_bf16 v[98:101], v[150:153], v[234:237], v[98:101]
	ds_read_b128 v[134:137], v229 offset:2048
	v_mfma_f32_16x16x32_bf16 v[70:73], v[150:153], v[238:241], v[70:73]
	ds_read_b128 v[138:141], v229 offset:4096
	v_mfma_f32_16x16x32_bf16 v[66:69], v[150:153], v[242:245], v[66:69]
	ds_read_b128 v[142:145], v229 offset:6144
	s_waitcnt vmcnt(6)
	v_mfma_f32_16x16x32_bf16 v[94:97], v[154:157], v[162:165], v[94:97]
	ds_write_b128 v222, v[38:41]
	v_mfma_f32_16x16x32_bf16 v[90:93], v[154:157], v[234:237], v[90:93]
	ds_write_b128 v222, v[46:49] offset:8192
	v_mfma_f32_16x16x32_bf16 v[62:65], v[154:157], v[238:241], v[62:65]
	ds_write_b128 v222, v[34:37] offset:16384
	v_mfma_f32_16x16x32_bf16 v[58:61], v[154:157], v[242:245], v[58:61]
	ds_write_b128 v222, v[42:45] offset:24576
	v_mfma_f32_16x16x32_bf16 v[86:89], v[158:161], v[162:165], v[86:89]
	ds_write_b128 v223, v[22:25]
	v_mfma_f32_16x16x32_bf16 v[82:85], v[158:161], v[234:237], v[82:85]
	ds_write_b128 v223, v[30:33] offset:8192
	v_mfma_f32_16x16x32_bf16 v[54:57], v[158:161], v[238:241], v[54:57]
	v_mfma_f32_16x16x32_bf16 v[50:53], v[158:161], v[242:245], v[50:53]
	s_cmp_gt_u32 s13, 11
	s_mov_b64 s[4:5], -1
	s_cbranch_scc0 .Lmydso__1051
	s_andn2_b64 vcc, exec, s[0:1]
	s_cbranch_vccnz .Lmydso__1050
	global_load_dwordx4 v[46:49], v[192:193], off
	global_load_dwordx4 v[34:37], v[194:195], off
	global_load_dwordx4 v[38:41], v[180:181], off
	global_load_dwordx4 v[22:25], v[182:183], off
	global_load_dwordx4 v[42:45], v[196:197], off
	global_load_dwordx4 v[30:33], v[198:199], off

.Lmyd_ocont:
	s_waitcnt lgkmcnt(6)
	v_mfma_f32_16x16x32_bf16 v[110:113], v[114:117], v[130:133], v[110:113]
	ds_read_b128 v[146:149], v226 offset:32768
	v_mfma_f32_16x16x32_bf16 v[106:109], v[114:117], v[134:137], v[106:109]
	ds_read_b128 v[150:153], v226 offset:34816
	v_mfma_f32_16x16x32_bf16 v[78:81], v[114:117], v[138:141], v[78:81]
	ds_read_b128 v[154:157], v226 offset:36864
	v_mfma_f32_16x16x32_bf16 v[74:77], v[114:117], v[142:145], v[74:77]
	ds_read_b128 v[158:161], v226 offset:38912
	v_mfma_f32_16x16x32_bf16 v[102:105], v[118:121], v[130:133], v[102:105]
	ds_read_b128 v[162:165], v230
	v_mfma_f32_16x16x32_bf16 v[98:101], v[118:121], v[134:137], v[98:101]
	ds_read_b128 v[234:237], v230 offset:2048
	v_mfma_f32_16x16x32_bf16 v[70:73], v[118:121], v[138:141], v[70:73]
	ds_read_b128 v[238:241], v230 offset:4096
	v_mfma_f32_16x16x32_bf16 v[66:69], v[118:121], v[142:145], v[66:69]
	ds_read_b128 v[242:245], v230 offset:6144
	v_mfma_f32_16x16x32_bf16 v[94:97], v[122:125], v[130:133], v[94:97]
	v_mfma_f32_16x16x32_bf16 v[90:93], v[122:125], v[134:137], v[90:93]
	v_mfma_f32_16x16x32_bf16 v[62:65], v[122:125], v[138:141], v[62:65]
	v_mfma_f32_16x16x32_bf16 v[58:61], v[122:125], v[142:145], v[58:61]
	v_mfma_f32_16x16x32_bf16 v[86:89], v[126:129], v[130:133], v[86:89]
	v_mfma_f32_16x16x32_bf16 v[82:85], v[126:129], v[134:137], v[82:85]
	v_mfma_f32_16x16x32_bf16 v[54:57], v[126:129], v[138:141], v[54:57]
	v_mfma_f32_16x16x32_bf16 v[50:53], v[126:129], v[142:145], v[50:53]
	s_add_i32 s13, s13, 2
	s_add_u32 s100, s100, 0x100
	s_addc_u32 s101, s101, 0
	s_add_u32 s98, s98, 0x100
	s_addc_u32 s99, s99, 0
	s_branch .Lmyd_even
.Lmyd_oddlast:
	v_mfma_f32_16x16x32_bf16 v[110:113], v[146:149], v[162:165], v[110:113]
	ds_read_b128 v[114:117], v224 offset:32768
	v_mfma_f32_16x16x32_bf16 v[106:109], v[146:149], v[234:237], v[106:109]
	ds_read_b128 v[118:121], v224 offset:34816
	v_mfma_f32_16x16x32_bf16 v[78:81], v[146:149], v[238:241], v[78:81]
	ds_read_b128 v[122:125], v224 offset:36864
	v_mfma_f32_16x16x32_bf16 v[74:77], v[146:149], v[242:245], v[74:77]
	ds_read_b128 v[126:129], v224 offset:38912
	v_mfma_f32_16x16x32_bf16 v[102:105], v[150:153], v[162:165], v[102:105]
	ds_read_b128 v[130:133], v229
	v_mfma_f32_16x16x32_bf16 v[98:101], v[150:153], v[234:237], v[98:101]
	ds_read_b128 v[134:137], v229 offset:2048
	v_mfma_f32_16x16x32_bf16 v[70:73], v[150:153], v[238:241], v[70:73]
	ds_read_b128 v[138:141], v229 offset:4096
	v_mfma_f32_16x16x32_bf16 v[66:69], v[150:153], v[242:245], v[66:69]
	ds_read_b128 v[142:145], v229 offset:6144
	v_mfma_f32_16x16x32_bf16 v[94:97], v[154:157], v[162:165], v[94:97]
	v_mfma_f32_16x16x32_bf16 v[90:93], v[154:157], v[234:237], v[90:93]
	v_mfma_f32_16x16x32_bf16 v[62:65], v[154:157], v[238:241], v[62:65]
	v_mfma_f32_16x16x32_bf16 v[58:61], v[154:157], v[242:245], v[58:61]
	v_mfma_f32_16x16x32_bf16 v[86:89], v[158:161], v[162:165], v[86:89]
	v_mfma_f32_16x16x32_bf16 v[82:85], v[158:161], v[234:237], v[82:85]
	v_mfma_f32_16x16x32_bf16 v[54:57], v[158:161], v[238:241], v[54:57]
	v_mfma_f32_16x16x32_bf16 v[50:53], v[158:161], v[242:245], v[50:53]
	s_waitcnt lgkmcnt(0)
	v_mfma_f32_16x16x32_bf16 v[110:113], v[114:117], v[130:133], v[110:113]
	ds_read_b128 v[146:149], v226 offset:32768
	v_mfma_f32_16x16x32_bf16 v[106:109], v[114:117], v[134:137], v[106:109]
	ds_read_b128 v[150:153], v226 offset:34816
	v_mfma_f32_16x16x32_bf16 v[78:81], v[114:117], v[138:141], v[78:81]
	ds_read_b128 v[154:157], v226 offset:36864
	v_mfma_f32_16x16x32_bf16 v[74:77], v[114:117], v[142:145], v[74:77]
	ds_read_b128 v[158:161], v226 offset:38912
	v_mfma_f32_16x16x32_bf16 v[102:105], v[118:121], v[130:133], v[102:105]
	ds_read_b128 v[162:165], v230
	v_mfma_f32_16x16x32_bf16 v[98:101], v[118:121], v[134:137], v[98:101]
	ds_read_b128 v[234:237], v230 offset:2048
	v_mfma_f32_16x16x32_bf16 v[70:73], v[118:121], v[138:141], v[70:73]
	ds_read_b128 v[238:241], v230 offset:4096
	v_mfma_f32_16x16x32_bf16 v[66:69], v[118:121], v[142:145], v[66:69]
	ds_read_b128 v[242:245], v230 offset:6144
	v_mfma_f32_16x16x32_bf16 v[94:97], v[122:125], v[130:133], v[94:97]
	v_mfma_f32_16x16x32_bf16 v[90:93], v[122:125], v[134:137], v[90:93]
	v_mfma_f32_16x16x32_bf16 v[62:65], v[122:125], v[138:141], v[62:65]
	v_mfma_f32_16x16x32_bf16 v[58:61], v[122:125], v[142:145], v[58:61]
	v_mfma_f32_16x16x32_bf16 v[86:89], v[126:129], v[130:133], v[86:89]
	v_mfma_f32_16x16x32_bf16 v[82:85], v[126:129], v[134:137], v[82:85]
	v_mfma_f32_16x16x32_bf16 v[54:57], v[126:129], v[138:141], v[54:57]
	v_mfma_f32_16x16x32_bf16 v[50:53], v[126:129], v[142:145], v[50:53]
	s_add_i32 s13, s13, 2
	s_add_u32 s100, s100, 0x100
	s_addc_u32 s101, s101, 0
	s_add_u32 s98, s98, 0x100
	s_addc_u32 s99, s99, 0
	s_waitcnt lgkmcnt(0)
	v_mfma_f32_16x16x32_bf16 v[110:113], v[146:149], v[162:165], v[110:113]
	v_mfma_f32_16x16x32_bf16 v[106:109], v[146:149], v[234:237], v[106:109]
	v_mfma_f32_16x16x32_bf16 v[78:81], v[146:149], v[238:241], v[78:81]
	v_mfma_f32_16x16x32_bf16 v[74:77], v[146:149], v[242:245], v[74:77]
	v_mfma_f32_16x16x32_bf16 v[102:105], v[150:153], v[162:165], v[102:105]
	v_mfma_f32_16x16x32_bf16 v[98:101], v[150:153], v[234:237], v[98:101]
	v_mfma_f32_16x16x32_bf16 v[70:73], v[150:153], v[238:241], v[70:73]
	v_mfma_f32_16x16x32_bf16 v[66:69], v[150:153], v[242:245], v[66:69]
	v_mfma_f32_16x16x32_bf16 v[94:97], v[154:157], v[162:165], v[94:97]
	v_mfma_f32_16x16x32_bf16 v[90:93], v[154:157], v[234:237], v[90:93]
	v_mfma_f32_16x16x32_bf16 v[62:65], v[154:157], v[238:241], v[62:65]
	v_mfma_f32_16x16x32_bf16 v[58:61], v[154:157], v[242:245], v[58:61]
	v_mfma_f32_16x16x32_bf16 v[86:89], v[158:161], v[162:165], v[86:89]
	v_mfma_f32_16x16x32_bf16 v[82:85], v[158:161], v[234:237], v[82:85]
	v_mfma_f32_16x16x32_bf16 v[54:57], v[158:161], v[238:241], v[54:57]
	v_mfma_f32_16x16x32_bf16 v[50:53], v[158:161], v[242:245], v[50:53]
	s_and_b64 vcc, exec, s[2:3]
	s_nop 7
	s_branch .LBB0_1053

.Lmye_even:
	s_waitcnt lgkmcnt(0)
	s_barrier
	v_mfma_f32_16x16x32_bf16 v[110:113], v[146:149], v[162:165], v[110:113]
	ds_read_b128 v[114:117], v224
	v_mfma_f32_16x16x32_bf16 v[106:109], v[146:149], v[166:169], v[106:109]
	ds_read_b128 v[118:121], v224 offset:2048
	v_mfma_f32_16x16x32_bf16 v[102:105], v[146:149], v[234:237], v[102:105]
	ds_read_b128 v[122:125], v224 offset:4096
	v_mfma_f32_16x16x32_bf16 v[98:101], v[146:149], v[238:241], v[98:101]
	ds_read_b128 v[126:129], v224 offset:6144
	v_mfma_f32_16x16x32_bf16 v[94:97], v[150:153], v[162:165], v[94:97]
	ds_read_b128 v[130:133], v225
	v_mfma_f32_16x16x32_bf16 v[90:93], v[150:153], v[166:169], v[90:93]
	ds_read_b128 v[134:137], v225 offset:2048
	v_mfma_f32_16x16x32_bf16 v[86:89], v[150:153], v[234:237], v[86:89]
	ds_read_b128 v[138:141], v225 offset:4096
	v_mfma_f32_16x16x32_bf16 v[82:85], v[150:153], v[238:241], v[82:85]
	ds_read_b128 v[142:145], v225 offset:6144
	s_cmp_gt_u32 s13, 28
	s_cbranch_scc0 .Lmye_ew6
	s_and_b64 vcc, exec, s[2:3]
	s_cbranch_vccnz .Lmye_ew6
	s_waitcnt vmcnt(0)
.Lmye_ew6:
	s_waitcnt vmcnt(6)
	v_mfma_f32_16x16x32_bf16 v[78:81], v[154:157], v[162:165], v[78:81]
	ds_write_b128 v222, v[6:9] offset:32768
	v_mfma_f32_16x16x32_bf16 v[74:77], v[154:157], v[166:169], v[74:77]
	ds_write_b128 v222, v[10:13] offset:40960
	v_mfma_f32_16x16x32_bf16 v[70:73], v[154:157], v[234:237], v[70:73]
	ds_write_b128 v222, v[18:21] offset:49152
	v_mfma_f32_16x16x32_bf16 v[66:69], v[154:157], v[238:241], v[66:69]
	ds_write_b128 v222, v[22:25] offset:57344
	v_mfma_f32_16x16x32_bf16 v[62:65], v[158:161], v[162:165], v[62:65]
	ds_write_b128 v228, v[26:29]
	v_mfma_f32_16x16x32_bf16 v[58:61], v[158:161], v[166:169], v[58:61]
	ds_write_b128 v228, v[34:37] offset:8192
	v_mfma_f32_16x16x32_bf16 v[54:57], v[158:161], v[234:237], v[54:57]
	v_mfma_f32_16x16x32_bf16 v[50:53], v[158:161], v[238:241], v[50:53]
	s_cmp_gt_u32 s13, 28
	s_mov_b64 s[4:5], -1
	s_cbranch_scc0 .Lmyese__1368
	s_andn2_b64 vcc, exec, s[2:3]
	s_cbranch_vccnz .Lmyese__1367
	global_load_dwordx4 v[10:13], v[186:187], off
	global_load_dwordx4 v[18:21], v[188:189], off
	global_load_dwordx4 v[6:9], v[182:183], off offset:128
	global_load_dwordx4 v[26:29], v[184:185], off offset:128
	global_load_dwordx4 v[22:25], v[190:191], off
	global_load_dwordx4 v[34:37], v[192:193], off

.Lmyese__1370:
	s_waitcnt lgkmcnt(6)
	v_mfma_f32_16x16x32_bf16 v[110:113], v[114:117], v[130:133], v[110:113]
	ds_read_b128 v[146:149], v226
	v_mfma_f32_16x16x32_bf16 v[106:109], v[114:117], v[134:137], v[106:109]
	ds_read_b128 v[150:153], v226 offset:2048
	v_mfma_f32_16x16x32_bf16 v[102:105], v[114:117], v[138:141], v[102:105]
	ds_read_b128 v[154:157], v226 offset:4096
	v_mfma_f32_16x16x32_bf16 v[98:101], v[114:117], v[142:145], v[98:101]
	ds_read_b128 v[158:161], v226 offset:6144
	v_mfma_f32_16x16x32_bf16 v[94:97], v[118:121], v[130:133], v[94:97]
	ds_read_b128 v[162:165], v227
	v_mfma_f32_16x16x32_bf16 v[90:93], v[118:121], v[134:137], v[90:93]
	ds_read_b128 v[166:169], v227 offset:2048
	v_mfma_f32_16x16x32_bf16 v[86:89], v[118:121], v[138:141], v[86:89]
	ds_read_b128 v[234:237], v227 offset:4096
	v_mfma_f32_16x16x32_bf16 v[82:85], v[118:121], v[142:145], v[82:85]
	ds_read_b128 v[238:241], v227 offset:6144
	v_mfma_f32_16x16x32_bf16 v[78:81], v[122:125], v[130:133], v[78:81]
	v_mfma_f32_16x16x32_bf16 v[74:77], v[122:125], v[134:137], v[74:77]
	v_mfma_f32_16x16x32_bf16 v[70:73], v[122:125], v[138:141], v[70:73]
	v_mfma_f32_16x16x32_bf16 v[66:69], v[122:125], v[142:145], v[66:69]
	v_mfma_f32_16x16x32_bf16 v[62:65], v[126:129], v[130:133], v[62:65]
	v_mfma_f32_16x16x32_bf16 v[58:61], v[126:129], v[134:137], v[58:61]
	v_mfma_f32_16x16x32_bf16 v[54:57], v[126:129], v[138:141], v[54:57]
	v_mfma_f32_16x16x32_bf16 v[50:53], v[126:129], v[142:145], v[50:53]
.Lmye_odd:
	s_waitcnt lgkmcnt(0)
	s_barrier
	s_cmp_gt_u32 s13, 29
	s_cselect_b64 s[4:5], -1, 0
	s_and_b64 vcc, exec, s[4:5]
	s_cbranch_vccnz .Lmye_oddlast
	v_mfma_f32_16x16x32_bf16 v[110:113], v[146:149], v[162:165], v[110:113]
	ds_read_b128 v[114:117], v224 offset:32768
	v_mfma_f32_16x16x32_bf16 v[106:109], v[146:149], v[166:169], v[106:109]
	ds_read_b128 v[118:121], v224 offset:34816
	v_mfma_f32_16x16x32_bf16 v[102:105], v[146:149], v[234:237], v[102:105]
	ds_read_b128 v[122:125], v224 offset:36864
	v_mfma_f32_16x16x32_bf16 v[98:101], v[146:149], v[238:241], v[98:101]
	ds_read_b128 v[126:129], v224 offset:38912
	v_mfma_f32_16x16x32_bf16 v[94:97], v[150:153], v[162:165], v[94:97]
	ds_read_b128 v[130:133], v229
	v_mfma_f32_16x16x32_bf16 v[90:93], v[150:153], v[166:169], v[90:93]
	ds_read_b128 v[134:137], v229 offset:2048
	v_mfma_f32_16x16x32_bf16 v[86:89], v[150:153], v[234:237], v[86:89]
	ds_read_b128 v[138:141], v229 offset:4096
	v_mfma_f32_16x16x32_bf16 v[82:85], v[150:153], v[238:241], v[82:85]
	ds_read_b128 v[142:145], v229 offset:6144
	s_waitcnt vmcnt(6)
	v_mfma_f32_16x16x32_bf16 v[78:81], v[154:157], v[162:165], v[78:81]
	ds_write_b128 v222, v[2:5]
	v_mfma_f32_16x16x32_bf16 v[74:77], v[154:157], v[166:169], v[74:77]
	ds_write_b128 v222, v[14:17] offset:8192
	v_mfma_f32_16x16x32_bf16 v[70:73], v[154:157], v[234:237], v[70:73]
	ds_write_b128 v222, v[30:33] offset:16384
	v_mfma_f32_16x16x32_bf16 v[66:69], v[154:157], v[238:241], v[66:69]
	ds_write_b128 v222, v[38:41] offset:24576
	v_mfma_f32_16x16x32_bf16 v[62:65], v[158:161], v[162:165], v[62:65]
	ds_write_b128 v223, v[42:45]
	v_mfma_f32_16x16x32_bf16 v[58:61], v[158:161], v[166:169], v[58:61]
	ds_write_b128 v223, v[46:49] offset:8192
	v_mfma_f32_16x16x32_bf16 v[54:57], v[158:161], v[234:237], v[54:57]
	v_mfma_f32_16x16x32_bf16 v[50:53], v[158:161], v[238:241], v[50:53]
	s_cmp_gt_u32 s13, 27
	s_mov_b64 s[6:7], -1
	s_cbranch_scc0 .Lmyeso__1375
	s_andn2_b64 vcc, exec, s[2:3]
	s_cbranch_vccnz .Lmyeso__1374
	global_load_dwordx4 v[14:17], v[194:195], off
	global_load_dwordx4 v[30:33], v[196:197], off
	global_load_dwordx4 v[2:5], v[182:183], off
	global_load_dwordx4 v[42:45], v[184:185], off
	global_load_dwordx4 v[38:41], v[198:199], off
	global_load_dwordx4 v[46:49], v[200:201], off

.Lmye_ocont:
	s_waitcnt lgkmcnt(6)
	v_mfma_f32_16x16x32_bf16 v[110:113], v[114:117], v[130:133], v[110:113]
	ds_read_b128 v[146:149], v226 offset:32768
	v_mfma_f32_16x16x32_bf16 v[106:109], v[114:117], v[134:137], v[106:109]
	ds_read_b128 v[150:153], v226 offset:34816
	v_mfma_f32_16x16x32_bf16 v[102:105], v[114:117], v[138:141], v[102:105]
	ds_read_b128 v[154:157], v226 offset:36864
	v_mfma_f32_16x16x32_bf16 v[98:101], v[114:117], v[142:145], v[98:101]
	ds_read_b128 v[158:161], v226 offset:38912
	v_mfma_f32_16x16x32_bf16 v[94:97], v[118:121], v[130:133], v[94:97]
	ds_read_b128 v[162:165], v230
	v_mfma_f32_16x16x32_bf16 v[90:93], v[118:121], v[134:137], v[90:93]
	ds_read_b128 v[166:169], v230 offset:2048
	v_mfma_f32_16x16x32_bf16 v[86:89], v[118:121], v[138:141], v[86:89]
	ds_read_b128 v[234:237], v230 offset:4096
	v_mfma_f32_16x16x32_bf16 v[82:85], v[118:121], v[142:145], v[82:85]
	ds_read_b128 v[238:241], v230 offset:6144
	v_mfma_f32_16x16x32_bf16 v[78:81], v[122:125], v[130:133], v[78:81]
	v_mfma_f32_16x16x32_bf16 v[74:77], v[122:125], v[134:137], v[74:77]
	v_mfma_f32_16x16x32_bf16 v[70:73], v[122:125], v[138:141], v[70:73]
	v_mfma_f32_16x16x32_bf16 v[66:69], v[122:125], v[142:145], v[66:69]
	v_mfma_f32_16x16x32_bf16 v[62:65], v[126:129], v[130:133], v[62:65]
	v_mfma_f32_16x16x32_bf16 v[58:61], v[126:129], v[134:137], v[58:61]
	v_mfma_f32_16x16x32_bf16 v[54:57], v[126:129], v[138:141], v[54:57]
	v_mfma_f32_16x16x32_bf16 v[50:53], v[126:129], v[142:145], v[50:53]
	s_add_i32 s13, s13, 2
	s_add_u32 s100, s100, 0x100
	s_addc_u32 s101, s101, 0
	s_add_u32 s98, s98, 0x100
	s_addc_u32 s99, s99, 0
	s_branch .Lmye_even
.Lmye_oddlast:
	v_mfma_f32_16x16x32_bf16 v[110:113], v[146:149], v[162:165], v[110:113]
	ds_read_b128 v[114:117], v224 offset:32768
	v_mfma_f32_16x16x32_bf16 v[106:109], v[146:149], v[166:169], v[106:109]
	ds_read_b128 v[118:121], v224 offset:34816
	v_mfma_f32_16x16x32_bf16 v[102:105], v[146:149], v[234:237], v[102:105]
	ds_read_b128 v[122:125], v224 offset:36864
	v_mfma_f32_16x16x32_bf16 v[98:101], v[146:149], v[238:241], v[98:101]
	ds_read_b128 v[126:129], v224 offset:38912
	v_mfma_f32_16x16x32_bf16 v[94:97], v[150:153], v[162:165], v[94:97]
	ds_read_b128 v[130:133], v229
	v_mfma_f32_16x16x32_bf16 v[90:93], v[150:153], v[166:169], v[90:93]
	ds_read_b128 v[134:137], v229 offset:2048
	v_mfma_f32_16x16x32_bf16 v[86:89], v[150:153], v[234:237], v[86:89]
	ds_read_b128 v[138:141], v229 offset:4096
	v_mfma_f32_16x16x32_bf16 v[82:85], v[150:153], v[238:241], v[82:85]
	ds_read_b128 v[142:145], v229 offset:6144
	v_mfma_f32_16x16x32_bf16 v[78:81], v[154:157], v[162:165], v[78:81]
	v_mfma_f32_16x16x32_bf16 v[74:77], v[154:157], v[166:169], v[74:77]
	v_mfma_f32_16x16x32_bf16 v[70:73], v[154:157], v[234:237], v[70:73]
	v_mfma_f32_16x16x32_bf16 v[66:69], v[154:157], v[238:241], v[66:69]
	v_mfma_f32_16x16x32_bf16 v[62:65], v[158:161], v[162:165], v[62:65]
	v_mfma_f32_16x16x32_bf16 v[58:61], v[158:161], v[166:169], v[58:61]
	v_mfma_f32_16x16x32_bf16 v[54:57], v[158:161], v[234:237], v[54:57]
	v_mfma_f32_16x16x32_bf16 v[50:53], v[158:161], v[238:241], v[50:53]
	s_waitcnt lgkmcnt(0)
	v_mfma_f32_16x16x32_bf16 v[110:113], v[114:117], v[130:133], v[110:113]
	ds_read_b128 v[146:149], v226 offset:32768
	v_mfma_f32_16x16x32_bf16 v[106:109], v[114:117], v[134:137], v[106:109]
	ds_read_b128 v[150:153], v226 offset:34816
	v_mfma_f32_16x16x32_bf16 v[102:105], v[114:117], v[138:141], v[102:105]
	ds_read_b128 v[154:157], v226 offset:36864
	v_mfma_f32_16x16x32_bf16 v[98:101], v[114:117], v[142:145], v[98:101]
	ds_read_b128 v[158:161], v226 offset:38912
	v_mfma_f32_16x16x32_bf16 v[94:97], v[118:121], v[130:133], v[94:97]
	ds_read_b128 v[162:165], v230
	v_mfma_f32_16x16x32_bf16 v[90:93], v[118:121], v[134:137], v[90:93]
	ds_read_b128 v[166:169], v230 offset:2048
	v_mfma_f32_16x16x32_bf16 v[86:89], v[118:121], v[138:141], v[86:89]
	ds_read_b128 v[234:237], v230 offset:4096
	v_mfma_f32_16x16x32_bf16 v[82:85], v[118:121], v[142:145], v[82:85]
	ds_read_b128 v[238:241], v230 offset:6144
	v_mfma_f32_16x16x32_bf16 v[78:81], v[122:125], v[130:133], v[78:81]
	v_mfma_f32_16x16x32_bf16 v[74:77], v[122:125], v[134:137], v[74:77]
	v_mfma_f32_16x16x32_bf16 v[70:73], v[122:125], v[138:141], v[70:73]
	v_mfma_f32_16x16x32_bf16 v[66:69], v[122:125], v[142:145], v[66:69]
	v_mfma_f32_16x16x32_bf16 v[62:65], v[126:129], v[130:133], v[62:65]
	v_mfma_f32_16x16x32_bf16 v[58:61], v[126:129], v[134:137], v[58:61]
	v_mfma_f32_16x16x32_bf16 v[54:57], v[126:129], v[138:141], v[54:57]
	v_mfma_f32_16x16x32_bf16 v[50:53], v[126:129], v[142:145], v[50:53]
	s_add_i32 s13, s13, 2
	s_add_u32 s100, s100, 0x100
	s_addc_u32 s101, s101, 0
	s_add_u32 s98, s98, 0x100
	s_addc_u32 s99, s99, 0
	s_waitcnt lgkmcnt(0)
	v_mfma_f32_16x16x32_bf16 v[110:113], v[146:149], v[162:165], v[110:113]
	v_mfma_f32_16x16x32_bf16 v[106:109], v[146:149], v[166:169], v[106:109]
	v_mfma_f32_16x16x32_bf16 v[102:105], v[146:149], v[234:237], v[102:105]
	v_mfma_f32_16x16x32_bf16 v[98:101], v[146:149], v[238:241], v[98:101]
	v_mfma_f32_16x16x32_bf16 v[94:97], v[150:153], v[162:165], v[94:97]
	v_mfma_f32_16x16x32_bf16 v[90:93], v[150:153], v[166:169], v[90:93]
	v_mfma_f32_16x16x32_bf16 v[86:89], v[150:153], v[234:237], v[86:89]
	v_mfma_f32_16x16x32_bf16 v[82:85], v[150:153], v[238:241], v[82:85]
	v_mfma_f32_16x16x32_bf16 v[78:81], v[154:157], v[162:165], v[78:81]
	v_mfma_f32_16x16x32_bf16 v[74:77], v[154:157], v[166:169], v[74:77]
	v_mfma_f32_16x16x32_bf16 v[70:73], v[154:157], v[234:237], v[70:73]
	v_mfma_f32_16x16x32_bf16 v[66:69], v[154:157], v[238:241], v[66:69]
	v_mfma_f32_16x16x32_bf16 v[62:65], v[158:161], v[162:165], v[62:65]
	v_mfma_f32_16x16x32_bf16 v[58:61], v[158:161], v[166:169], v[58:61]
	v_mfma_f32_16x16x32_bf16 v[54:57], v[158:161], v[234:237], v[54:57]
	v_mfma_f32_16x16x32_bf16 v[50:53], v[158:161], v[238:241], v[50:53]
	s_and_b64 vcc, exec, s[4:5]
	s_nop 7
	s_branch .LBB0_1359

.Lmyf_even:
	s_waitcnt lgkmcnt(0)
	s_barrier
	v_mfma_f32_16x16x32_bf16 v[108:111], v[160:163], v[144:147], v[108:111]
	ds_read_b128 v[112:115], v215
	v_mfma_f32_16x16x32_bf16 v[104:107], v[164:167], v[144:147], v[104:107]
	ds_read_b128 v[116:119], v215 offset:2048
	v_mfma_f32_16x16x32_bf16 v[100:103], v[224:227], v[144:147], v[100:103]
	ds_read_b128 v[120:123], v215 offset:4096
	v_mfma_f32_16x16x32_bf16 v[96:99], v[228:231], v[144:147], v[96:99]
	ds_read_b128 v[124:127], v215 offset:6144
	v_mfma_f32_16x16x32_bf16 v[92:95], v[160:163], v[148:151], v[92:95]
	ds_read_b128 v[128:131], v216
	v_mfma_f32_16x16x32_bf16 v[88:91], v[164:167], v[148:151], v[88:91]
	ds_read_b128 v[132:135], v216 offset:2048
	v_mfma_f32_16x16x32_bf16 v[84:87], v[224:227], v[148:151], v[84:87]
	ds_read_b128 v[136:139], v216 offset:4096
	v_mfma_f32_16x16x32_bf16 v[80:83], v[228:231], v[148:151], v[80:83]
	ds_read_b128 v[140:143], v216 offset:6144
	s_cmp_gt_u32 s22, 12
	s_cbranch_scc0 .Lmyf_ew6
	s_and_b64 vcc, exec, s[8:9]
	s_cbranch_vccnz .Lmyf_ew6
	s_waitcnt vmcnt(0)
.Lmyf_ew6:
	s_waitcnt vmcnt(6)
	v_mfma_f32_16x16x32_bf16 v[76:79], v[160:163], v[152:155], v[76:79]
	ds_write_b128 v173, v[0:3] offset:32768
	v_mfma_f32_16x16x32_bf16 v[72:75], v[164:167], v[152:155], v[72:75]
	ds_write_b128 v173, v[4:7] offset:40960
	v_mfma_f32_16x16x32_bf16 v[68:71], v[224:227], v[152:155], v[68:71]
	ds_write_b128 v173, v[8:11] offset:49152
	v_mfma_f32_16x16x32_bf16 v[64:67], v[228:231], v[152:155], v[64:67]
	ds_write_b128 v173, v[12:15] offset:57344
	v_mfma_f32_16x16x32_bf16 v[60:63], v[160:163], v[156:159], v[60:63]
	ds_write_b128 v219, v[16:19]
	v_mfma_f32_16x16x32_bf16 v[56:59], v[164:167], v[156:159], v[56:59]
	ds_write_b128 v219, v[24:27] offset:8192
	v_mfma_f32_16x16x32_bf16 v[52:55], v[224:227], v[156:159], v[52:55]
	v_mfma_f32_16x16x32_bf16 v[48:51], v[228:231], v[156:159], v[48:51]
	s_cmp_gt_u32 s22, 12
	s_mov_b64 s[10:11], -1
	s_cbranch_scc0 .Lmyfse__1496
	s_andn2_b64 vcc, exec, s[8:9]
	s_cbranch_vccnz .Lmyfse__1495
	global_load_dwordx4 v[4:7], v[190:191], off
	global_load_dwordx4 v[8:11], v[192:193], off
	global_load_dwordx4 v[0:3], v[186:187], off offset:128
	global_load_dwordx4 v[16:19], v[188:189], off offset:128
	global_load_dwordx4 v[12:15], v[194:195], off
	global_load_dwordx4 v[24:27], v[196:197], off

.Lmyfse__1498:
	s_waitcnt lgkmcnt(6)
	v_mfma_f32_16x16x32_bf16 v[108:111], v[128:131], v[112:115], v[108:111]
	ds_read_b128 v[144:147], v217
	v_mfma_f32_16x16x32_bf16 v[104:107], v[132:135], v[112:115], v[104:107]
	ds_read_b128 v[148:151], v217 offset:2048
	v_mfma_f32_16x16x32_bf16 v[100:103], v[136:139], v[112:115], v[100:103]
	ds_read_b128 v[152:155], v217 offset:4096
	v_mfma_f32_16x16x32_bf16 v[96:99], v[140:143], v[112:115], v[96:99]
	ds_read_b128 v[156:159], v217 offset:6144
	v_mfma_f32_16x16x32_bf16 v[92:95], v[128:131], v[116:119], v[92:95]
	ds_read_b128 v[160:163], v218
	v_mfma_f32_16x16x32_bf16 v[88:91], v[132:135], v[116:119], v[88:91]
	ds_read_b128 v[164:167], v218 offset:2048
	v_mfma_f32_16x16x32_bf16 v[84:87], v[136:139], v[116:119], v[84:87]
	ds_read_b128 v[224:227], v218 offset:4096
	v_mfma_f32_16x16x32_bf16 v[80:83], v[140:143], v[116:119], v[80:83]
	ds_read_b128 v[228:231], v218 offset:6144
	v_mfma_f32_16x16x32_bf16 v[76:79], v[128:131], v[120:123], v[76:79]
	v_mfma_f32_16x16x32_bf16 v[72:75], v[132:135], v[120:123], v[72:75]
	v_mfma_f32_16x16x32_bf16 v[68:71], v[136:139], v[120:123], v[68:71]
	v_mfma_f32_16x16x32_bf16 v[64:67], v[140:143], v[120:123], v[64:67]
	v_mfma_f32_16x16x32_bf16 v[60:63], v[128:131], v[124:127], v[60:63]
	v_mfma_f32_16x16x32_bf16 v[56:59], v[132:135], v[124:127], v[56:59]
	v_mfma_f32_16x16x32_bf16 v[52:55], v[136:139], v[124:127], v[52:55]
	v_mfma_f32_16x16x32_bf16 v[48:51], v[140:143], v[124:127], v[48:51]
.Lmyf_odd:
	s_waitcnt lgkmcnt(0)
	s_barrier
	s_cmp_gt_u32 s22, 13
	s_cselect_b64 s[10:11], -1, 0
	s_and_b64 vcc, exec, s[10:11]
	s_cbranch_vccnz .Lmyf_oddlast
	v_mfma_f32_16x16x32_bf16 v[108:111], v[160:163], v[144:147], v[108:111]
	ds_read_b128 v[112:115], v215 offset:32768
	v_mfma_f32_16x16x32_bf16 v[104:107], v[164:167], v[144:147], v[104:107]
	ds_read_b128 v[116:119], v215 offset:34816
	v_mfma_f32_16x16x32_bf16 v[100:103], v[224:227], v[144:147], v[100:103]
	ds_read_b128 v[120:123], v215 offset:36864
	v_mfma_f32_16x16x32_bf16 v[96:99], v[228:231], v[144:147], v[96:99]
	ds_read_b128 v[124:127], v215 offset:38912
	v_mfma_f32_16x16x32_bf16 v[92:95], v[160:163], v[148:151], v[92:95]
	ds_read_b128 v[128:131], v220
	v_mfma_f32_16x16x32_bf16 v[88:91], v[164:167], v[148:151], v[88:91]
	ds_read_b128 v[132:135], v220 offset:2048
	v_mfma_f32_16x16x32_bf16 v[84:87], v[224:227], v[148:151], v[84:87]
	ds_read_b128 v[136:139], v220 offset:4096
	v_mfma_f32_16x16x32_bf16 v[80:83], v[228:231], v[148:151], v[80:83]
	ds_read_b128 v[140:143], v220 offset:6144
	s_waitcnt vmcnt(6)
	v_mfma_f32_16x16x32_bf16 v[76:79], v[160:163], v[152:155], v[76:79]
	ds_write_b128 v173, v[36:39]
	v_mfma_f32_16x16x32_bf16 v[72:75], v[164:167], v[152:155], v[72:75]
	ds_write_b128 v173, v[44:47] offset:8192
	v_mfma_f32_16x16x32_bf16 v[68:71], v[224:227], v[152:155], v[68:71]
	ds_write_b128 v173, v[32:35] offset:16384
	v_mfma_f32_16x16x32_bf16 v[64:67], v[228:231], v[152:155], v[64:67]
	ds_write_b128 v173, v[40:43] offset:24576
	v_mfma_f32_16x16x32_bf16 v[60:63], v[160:163], v[156:159], v[60:63]
	ds_write_b128 v214, v[20:23]
	v_mfma_f32_16x16x32_bf16 v[56:59], v[164:167], v[156:159], v[56:59]
	ds_write_b128 v214, v[28:31] offset:8192
	v_mfma_f32_16x16x32_bf16 v[52:55], v[224:227], v[156:159], v[52:55]
	v_mfma_f32_16x16x32_bf16 v[48:51], v[228:231], v[156:159], v[48:51]
	s_cmp_gt_u32 s22, 11
	s_mov_b64 s[12:13], -1
	s_cbranch_scc0 .Lmyfso__1503
	s_andn2_b64 vcc, exec, s[8:9]
	s_cbranch_vccnz .Lmyfso__1502
	global_load_dwordx4 v[44:47], v[198:199], off
	global_load_dwordx4 v[32:35], v[200:201], off
	global_load_dwordx4 v[36:39], v[186:187], off
	global_load_dwordx4 v[20:23], v[188:189], off
	global_load_dwordx4 v[40:43], v[202:203], off
	global_load_dwordx4 v[28:31], v[204:205], off

.Lmyf_ocont:
	s_waitcnt lgkmcnt(6)
	v_mfma_f32_16x16x32_bf16 v[108:111], v[128:131], v[112:115], v[108:111]
	ds_read_b128 v[144:147], v217 offset:32768
	v_mfma_f32_16x16x32_bf16 v[104:107], v[132:135], v[112:115], v[104:107]
	ds_read_b128 v[148:151], v217 offset:34816
	v_mfma_f32_16x16x32_bf16 v[100:103], v[136:139], v[112:115], v[100:103]
	ds_read_b128 v[152:155], v217 offset:36864
	v_mfma_f32_16x16x32_bf16 v[96:99], v[140:143], v[112:115], v[96:99]
	ds_read_b128 v[156:159], v217 offset:38912
	v_mfma_f32_16x16x32_bf16 v[92:95], v[128:131], v[116:119], v[92:95]
	ds_read_b128 v[160:163], v221
	v_mfma_f32_16x16x32_bf16 v[88:91], v[132:135], v[116:119], v[88:91]
	ds_read_b128 v[164:167], v221 offset:2048
	v_mfma_f32_16x16x32_bf16 v[84:87], v[136:139], v[116:119], v[84:87]
	ds_read_b128 v[224:227], v221 offset:4096
	v_mfma_f32_16x16x32_bf16 v[80:83], v[140:143], v[116:119], v[80:83]
	ds_read_b128 v[228:231], v221 offset:6144
	v_mfma_f32_16x16x32_bf16 v[76:79], v[128:131], v[120:123], v[76:79]
	v_mfma_f32_16x16x32_bf16 v[72:75], v[132:135], v[120:123], v[72:75]
	v_mfma_f32_16x16x32_bf16 v[68:71], v[136:139], v[120:123], v[68:71]
	v_mfma_f32_16x16x32_bf16 v[64:67], v[140:143], v[120:123], v[64:67]
	v_mfma_f32_16x16x32_bf16 v[60:63], v[128:131], v[124:127], v[60:63]
	v_mfma_f32_16x16x32_bf16 v[56:59], v[132:135], v[124:127], v[56:59]
	v_mfma_f32_16x16x32_bf16 v[52:55], v[136:139], v[124:127], v[52:55]
	v_mfma_f32_16x16x32_bf16 v[48:51], v[140:143], v[124:127], v[48:51]
	s_add_i32 s22, s22, 2
	s_add_u32 s100, s100, 0x100
	s_addc_u32 s101, s101, 0
	s_add_u32 s98, s98, 0x100
	s_addc_u32 s99, s99, 0
	s_branch .Lmyf_even
.Lmyf_oddlast:
	v_mfma_f32_16x16x32_bf16 v[108:111], v[160:163], v[144:147], v[108:111]
	ds_read_b128 v[112:115], v215 offset:32768
	v_mfma_f32_16x16x32_bf16 v[104:107], v[164:167], v[144:147], v[104:107]
	ds_read_b128 v[116:119], v215 offset:34816
	v_mfma_f32_16x16x32_bf16 v[100:103], v[224:227], v[144:147], v[100:103]
	ds_read_b128 v[120:123], v215 offset:36864
	v_mfma_f32_16x16x32_bf16 v[96:99], v[228:231], v[144:147], v[96:99]
	ds_read_b128 v[124:127], v215 offset:38912
	v_mfma_f32_16x16x32_bf16 v[92:95], v[160:163], v[148:151], v[92:95]
	ds_read_b128 v[128:131], v220
	v_mfma_f32_16x16x32_bf16 v[88:91], v[164:167], v[148:151], v[88:91]
	ds_read_b128 v[132:135], v220 offset:2048
	v_mfma_f32_16x16x32_bf16 v[84:87], v[224:227], v[148:151], v[84:87]
	ds_read_b128 v[136:139], v220 offset:4096
	v_mfma_f32_16x16x32_bf16 v[80:83], v[228:231], v[148:151], v[80:83]
	ds_read_b128 v[140:143], v220 offset:6144
	v_mfma_f32_16x16x32_bf16 v[76:79], v[160:163], v[152:155], v[76:79]
	v_mfma_f32_16x16x32_bf16 v[72:75], v[164:167], v[152:155], v[72:75]
	v_mfma_f32_16x16x32_bf16 v[68:71], v[224:227], v[152:155], v[68:71]
	v_mfma_f32_16x16x32_bf16 v[64:67], v[228:231], v[152:155], v[64:67]
	v_mfma_f32_16x16x32_bf16 v[60:63], v[160:163], v[156:159], v[60:63]
	v_mfma_f32_16x16x32_bf16 v[56:59], v[164:167], v[156:159], v[56:59]
	v_mfma_f32_16x16x32_bf16 v[52:55], v[224:227], v[156:159], v[52:55]
	v_mfma_f32_16x16x32_bf16 v[48:51], v[228:231], v[156:159], v[48:51]
	s_waitcnt lgkmcnt(0)
	v_mfma_f32_16x16x32_bf16 v[108:111], v[128:131], v[112:115], v[108:111]
	ds_read_b128 v[144:147], v217 offset:32768
	v_mfma_f32_16x16x32_bf16 v[104:107], v[132:135], v[112:115], v[104:107]
	ds_read_b128 v[148:151], v217 offset:34816
	v_mfma_f32_16x16x32_bf16 v[100:103], v[136:139], v[112:115], v[100:103]
	ds_read_b128 v[152:155], v217 offset:36864
	v_mfma_f32_16x16x32_bf16 v[96:99], v[140:143], v[112:115], v[96:99]
	ds_read_b128 v[156:159], v217 offset:38912
	v_mfma_f32_16x16x32_bf16 v[92:95], v[128:131], v[116:119], v[92:95]
	ds_read_b128 v[160:163], v221
	v_mfma_f32_16x16x32_bf16 v[88:91], v[132:135], v[116:119], v[88:91]
	ds_read_b128 v[164:167], v221 offset:2048
	v_mfma_f32_16x16x32_bf16 v[84:87], v[136:139], v[116:119], v[84:87]
	ds_read_b128 v[224:227], v221 offset:4096
	v_mfma_f32_16x16x32_bf16 v[80:83], v[140:143], v[116:119], v[80:83]
	ds_read_b128 v[228:231], v221 offset:6144
	v_mfma_f32_16x16x32_bf16 v[76:79], v[128:131], v[120:123], v[76:79]
	v_mfma_f32_16x16x32_bf16 v[72:75], v[132:135], v[120:123], v[72:75]
	v_mfma_f32_16x16x32_bf16 v[68:71], v[136:139], v[120:123], v[68:71]
	v_mfma_f32_16x16x32_bf16 v[64:67], v[140:143], v[120:123], v[64:67]
	v_mfma_f32_16x16x32_bf16 v[60:63], v[128:131], v[124:127], v[60:63]
	v_mfma_f32_16x16x32_bf16 v[56:59], v[132:135], v[124:127], v[56:59]
	v_mfma_f32_16x16x32_bf16 v[52:55], v[136:139], v[124:127], v[52:55]
	v_mfma_f32_16x16x32_bf16 v[48:51], v[140:143], v[124:127], v[48:51]
	s_add_i32 s22, s22, 2
	s_add_u32 s100, s100, 0x100
	s_addc_u32 s101, s101, 0
	s_add_u32 s98, s98, 0x100
	s_addc_u32 s99, s99, 0
	s_waitcnt lgkmcnt(0)
	v_mfma_f32_16x16x32_bf16 v[108:111], v[160:163], v[144:147], v[108:111]
	v_mfma_f32_16x16x32_bf16 v[104:107], v[164:167], v[144:147], v[104:107]
	v_mfma_f32_16x16x32_bf16 v[100:103], v[224:227], v[144:147], v[100:103]
	v_mfma_f32_16x16x32_bf16 v[96:99], v[228:231], v[144:147], v[96:99]
	v_mfma_f32_16x16x32_bf16 v[92:95], v[160:163], v[148:151], v[92:95]
	v_mfma_f32_16x16x32_bf16 v[88:91], v[164:167], v[148:151], v[88:91]
	v_mfma_f32_16x16x32_bf16 v[84:87], v[224:227], v[148:151], v[84:87]
	v_mfma_f32_16x16x32_bf16 v[80:83], v[228:231], v[148:151], v[80:83]
	v_mfma_f32_16x16x32_bf16 v[76:79], v[160:163], v[152:155], v[76:79]
	v_mfma_f32_16x16x32_bf16 v[72:75], v[164:167], v[152:155], v[72:75]
	v_mfma_f32_16x16x32_bf16 v[68:71], v[224:227], v[152:155], v[68:71]
	v_mfma_f32_16x16x32_bf16 v[64:67], v[228:231], v[152:155], v[64:67]
	v_mfma_f32_16x16x32_bf16 v[60:63], v[160:163], v[156:159], v[60:63]
	v_mfma_f32_16x16x32_bf16 v[56:59], v[164:167], v[156:159], v[56:59]
	v_mfma_f32_16x16x32_bf16 v[52:55], v[224:227], v[156:159], v[52:55]
	v_mfma_f32_16x16x32_bf16 v[48:51], v[228:231], v[156:159], v[48:51]
	s_and_b64 vcc, exec, s[10:11]
	s_nop 7
	s_branch .LBB0_1487

.Lmyg_even:
	s_waitcnt lgkmcnt(0)
	s_barrier
	v_mfma_f32_16x16x32_bf16 v[108:111], v[144:147], v[160:163], v[108:111]
	ds_read_b128 v[112:115], v214
	v_mfma_f32_16x16x32_bf16 v[104:107], v[144:147], v[164:167], v[104:107]
	ds_read_b128 v[116:119], v214 offset:2048
	v_mfma_f32_16x16x32_bf16 v[100:103], v[144:147], v[224:227], v[100:103]
	ds_read_b128 v[120:123], v214 offset:4096
	v_mfma_f32_16x16x32_bf16 v[96:99], v[144:147], v[228:231], v[96:99]
	ds_read_b128 v[124:127], v214 offset:6144
	v_mfma_f32_16x16x32_bf16 v[92:95], v[148:151], v[160:163], v[92:95]
	ds_read_b128 v[128:131], v215
	v_mfma_f32_16x16x32_bf16 v[88:91], v[148:151], v[164:167], v[88:91]
	ds_read_b128 v[132:135], v215 offset:2048
	v_mfma_f32_16x16x32_bf16 v[84:87], v[148:151], v[224:227], v[84:87]
	ds_read_b128 v[136:139], v215 offset:4096
	v_mfma_f32_16x16x32_bf16 v[80:83], v[148:151], v[228:231], v[80:83]
	ds_read_b128 v[140:143], v215 offset:6144
	s_cmp_gt_u32 s19, 60
	s_cbranch_scc0 .Lmyg_ew6
	s_and_b64 vcc, exec, s[8:9]
	s_cbranch_vccnz .Lmyg_ew6
	s_waitcnt vmcnt(0)
.Lmyg_ew6:
	s_waitcnt vmcnt(6)
	v_mfma_f32_16x16x32_bf16 v[76:79], v[152:155], v[160:163], v[76:79]
	ds_write_b128 v204, v[4:7] offset:32768
	v_mfma_f32_16x16x32_bf16 v[72:75], v[152:155], v[164:167], v[72:75]
	ds_write_b128 v204, v[8:11] offset:40960
	v_mfma_f32_16x16x32_bf16 v[68:71], v[152:155], v[224:227], v[68:71]
	ds_write_b128 v204, v[16:19] offset:49152
	v_mfma_f32_16x16x32_bf16 v[64:67], v[152:155], v[228:231], v[64:67]
	ds_write_b128 v204, v[20:23] offset:57344
	v_mfma_f32_16x16x32_bf16 v[60:63], v[156:159], v[160:163], v[60:63]
	ds_write_b128 v218, v[24:27]
	v_mfma_f32_16x16x32_bf16 v[56:59], v[156:159], v[164:167], v[56:59]
	ds_write_b128 v218, v[32:35] offset:8192
	v_mfma_f32_16x16x32_bf16 v[52:55], v[156:159], v[224:227], v[52:55]
	v_mfma_f32_16x16x32_bf16 v[48:51], v[156:159], v[228:231], v[48:51]
	s_cmp_gt_u32 s19, 60
	s_mov_b64 s[10:11], -1
	s_cbranch_scc0 .Lmygse__1568
	s_andn2_b64 vcc, exec, s[8:9]
	s_cbranch_vccnz .Lmygse__1567
	global_load_dwordx4 v[8:11], v[188:189], off
	global_load_dwordx4 v[16:19], v[190:191], off
	global_load_dwordx4 v[4:7], v[184:185], off offset:128
	global_load_dwordx4 v[24:27], v[186:187], off offset:128
	global_load_dwordx4 v[20:23], v[192:193], off
	global_load_dwordx4 v[32:35], v[194:195], off

.Lmygse__1570:
	s_waitcnt lgkmcnt(6)
	v_mfma_f32_16x16x32_bf16 v[108:111], v[112:115], v[128:131], v[108:111]
	ds_read_b128 v[144:147], v216
	v_mfma_f32_16x16x32_bf16 v[104:107], v[112:115], v[132:135], v[104:107]
	ds_read_b128 v[148:151], v216 offset:2048
	v_mfma_f32_16x16x32_bf16 v[100:103], v[112:115], v[136:139], v[100:103]
	ds_read_b128 v[152:155], v216 offset:4096
	v_mfma_f32_16x16x32_bf16 v[96:99], v[112:115], v[140:143], v[96:99]
	ds_read_b128 v[156:159], v216 offset:6144
	v_mfma_f32_16x16x32_bf16 v[92:95], v[116:119], v[128:131], v[92:95]
	ds_read_b128 v[160:163], v217
	v_mfma_f32_16x16x32_bf16 v[88:91], v[116:119], v[132:135], v[88:91]
	ds_read_b128 v[164:167], v217 offset:2048
	v_mfma_f32_16x16x32_bf16 v[84:87], v[116:119], v[136:139], v[84:87]
	ds_read_b128 v[224:227], v217 offset:4096
	v_mfma_f32_16x16x32_bf16 v[80:83], v[116:119], v[140:143], v[80:83]
	ds_read_b128 v[228:231], v217 offset:6144
	v_mfma_f32_16x16x32_bf16 v[76:79], v[120:123], v[128:131], v[76:79]
	v_mfma_f32_16x16x32_bf16 v[72:75], v[120:123], v[132:135], v[72:75]
	v_mfma_f32_16x16x32_bf16 v[68:71], v[120:123], v[136:139], v[68:71]
	v_mfma_f32_16x16x32_bf16 v[64:67], v[120:123], v[140:143], v[64:67]
	v_mfma_f32_16x16x32_bf16 v[60:63], v[124:127], v[128:131], v[60:63]
	v_mfma_f32_16x16x32_bf16 v[56:59], v[124:127], v[132:135], v[56:59]
	v_mfma_f32_16x16x32_bf16 v[52:55], v[124:127], v[136:139], v[52:55]
	v_mfma_f32_16x16x32_bf16 v[48:51], v[124:127], v[140:143], v[48:51]
.Lmyg_odd:
	s_waitcnt lgkmcnt(0)
	s_barrier
	s_cmp_gt_u32 s19, 61
	s_cselect_b64 s[10:11], -1, 0
	s_and_b64 vcc, exec, s[10:11]
	s_cbranch_vccnz .Lmyg_oddlast
	v_mfma_f32_16x16x32_bf16 v[108:111], v[144:147], v[160:163], v[108:111]
	ds_read_b128 v[112:115], v214 offset:32768
	v_mfma_f32_16x16x32_bf16 v[104:107], v[144:147], v[164:167], v[104:107]
	ds_read_b128 v[116:119], v214 offset:34816
	v_mfma_f32_16x16x32_bf16 v[100:103], v[144:147], v[224:227], v[100:103]
	ds_read_b128 v[120:123], v214 offset:36864
	v_mfma_f32_16x16x32_bf16 v[96:99], v[144:147], v[228:231], v[96:99]
	ds_read_b128 v[124:127], v214 offset:38912
	v_mfma_f32_16x16x32_bf16 v[92:95], v[148:151], v[160:163], v[92:95]
	ds_read_b128 v[128:131], v219
	v_mfma_f32_16x16x32_bf16 v[88:91], v[148:151], v[164:167], v[88:91]
	ds_read_b128 v[132:135], v219 offset:2048
	v_mfma_f32_16x16x32_bf16 v[84:87], v[148:151], v[224:227], v[84:87]
	ds_read_b128 v[136:139], v219 offset:4096
	v_mfma_f32_16x16x32_bf16 v[80:83], v[148:151], v[228:231], v[80:83]
	ds_read_b128 v[140:143], v219 offset:6144
	s_waitcnt vmcnt(6)
	v_mfma_f32_16x16x32_bf16 v[76:79], v[152:155], v[160:163], v[76:79]
	ds_write_b128 v204, v[0:3]
	v_mfma_f32_16x16x32_bf16 v[72:75], v[152:155], v[164:167], v[72:75]
	ds_write_b128 v204, v[12:15] offset:8192
	v_mfma_f32_16x16x32_bf16 v[68:71], v[152:155], v[224:227], v[68:71]
	ds_write_b128 v204, v[28:31] offset:16384
	v_mfma_f32_16x16x32_bf16 v[64:67], v[152:155], v[228:231], v[64:67]
	ds_write_b128 v204, v[36:39] offset:24576
	v_mfma_f32_16x16x32_bf16 v[60:63], v[156:159], v[160:163], v[60:63]
	ds_write_b128 v205, v[40:43]
	v_mfma_f32_16x16x32_bf16 v[56:59], v[156:159], v[164:167], v[56:59]
	ds_write_b128 v205, v[44:47] offset:8192
	v_mfma_f32_16x16x32_bf16 v[52:55], v[156:159], v[224:227], v[52:55]
	v_mfma_f32_16x16x32_bf16 v[48:51], v[156:159], v[228:231], v[48:51]
	s_cmp_gt_u32 s19, 59
	s_mov_b64 s[12:13], -1
	s_cbranch_scc0 .Lmygso__1575
	s_andn2_b64 vcc, exec, s[8:9]
	s_cbranch_vccnz .Lmygso__1574
	global_load_dwordx4 v[12:15], v[196:197], off
	global_load_dwordx4 v[28:31], v[198:199], off
	global_load_dwordx4 v[0:3], v[184:185], off
	global_load_dwordx4 v[40:43], v[186:187], off
	global_load_dwordx4 v[36:39], v[200:201], off
	global_load_dwordx4 v[44:47], v[202:203], off

.Lmyg_ocont:
	s_waitcnt lgkmcnt(6)
	v_mfma_f32_16x16x32_bf16 v[108:111], v[112:115], v[128:131], v[108:111]
	ds_read_b128 v[144:147], v216 offset:32768
	v_mfma_f32_16x16x32_bf16 v[104:107], v[112:115], v[132:135], v[104:107]
	ds_read_b128 v[148:151], v216 offset:34816
	v_mfma_f32_16x16x32_bf16 v[100:103], v[112:115], v[136:139], v[100:103]
	ds_read_b128 v[152:155], v216 offset:36864
	v_mfma_f32_16x16x32_bf16 v[96:99], v[112:115], v[140:143], v[96:99]
	ds_read_b128 v[156:159], v216 offset:38912
	v_mfma_f32_16x16x32_bf16 v[92:95], v[116:119], v[128:131], v[92:95]
	ds_read_b128 v[160:163], v220
	v_mfma_f32_16x16x32_bf16 v[88:91], v[116:119], v[132:135], v[88:91]
	ds_read_b128 v[164:167], v220 offset:2048
	v_mfma_f32_16x16x32_bf16 v[84:87], v[116:119], v[136:139], v[84:87]
	ds_read_b128 v[224:227], v220 offset:4096
	v_mfma_f32_16x16x32_bf16 v[80:83], v[116:119], v[140:143], v[80:83]
	ds_read_b128 v[228:231], v220 offset:6144
	v_mfma_f32_16x16x32_bf16 v[76:79], v[120:123], v[128:131], v[76:79]
	v_mfma_f32_16x16x32_bf16 v[72:75], v[120:123], v[132:135], v[72:75]
	v_mfma_f32_16x16x32_bf16 v[68:71], v[120:123], v[136:139], v[68:71]
	v_mfma_f32_16x16x32_bf16 v[64:67], v[120:123], v[140:143], v[64:67]
	v_mfma_f32_16x16x32_bf16 v[60:63], v[124:127], v[128:131], v[60:63]
	v_mfma_f32_16x16x32_bf16 v[56:59], v[124:127], v[132:135], v[56:59]
	v_mfma_f32_16x16x32_bf16 v[52:55], v[124:127], v[136:139], v[52:55]
	v_mfma_f32_16x16x32_bf16 v[48:51], v[124:127], v[140:143], v[48:51]
	s_add_i32 s19, s19, 2
	s_add_u32 s100, s100, 0x100
	s_addc_u32 s101, s101, 0
	s_add_u32 s98, s98, 0x100
	s_addc_u32 s99, s99, 0
	s_branch .Lmyg_even
.Lmyg_oddlast:
	v_mfma_f32_16x16x32_bf16 v[108:111], v[144:147], v[160:163], v[108:111]
	ds_read_b128 v[112:115], v214 offset:32768
	v_mfma_f32_16x16x32_bf16 v[104:107], v[144:147], v[164:167], v[104:107]
	ds_read_b128 v[116:119], v214 offset:34816
	v_mfma_f32_16x16x32_bf16 v[100:103], v[144:147], v[224:227], v[100:103]
	ds_read_b128 v[120:123], v214 offset:36864
	v_mfma_f32_16x16x32_bf16 v[96:99], v[144:147], v[228:231], v[96:99]
	ds_read_b128 v[124:127], v214 offset:38912
	v_mfma_f32_16x16x32_bf16 v[92:95], v[148:151], v[160:163], v[92:95]
	ds_read_b128 v[128:131], v219
	v_mfma_f32_16x16x32_bf16 v[88:91], v[148:151], v[164:167], v[88:91]
	ds_read_b128 v[132:135], v219 offset:2048
	v_mfma_f32_16x16x32_bf16 v[84:87], v[148:151], v[224:227], v[84:87]
	ds_read_b128 v[136:139], v219 offset:4096
	v_mfma_f32_16x16x32_bf16 v[80:83], v[148:151], v[228:231], v[80:83]
	ds_read_b128 v[140:143], v219 offset:6144
	v_mfma_f32_16x16x32_bf16 v[76:79], v[152:155], v[160:163], v[76:79]
	v_mfma_f32_16x16x32_bf16 v[72:75], v[152:155], v[164:167], v[72:75]
	v_mfma_f32_16x16x32_bf16 v[68:71], v[152:155], v[224:227], v[68:71]
	v_mfma_f32_16x16x32_bf16 v[64:67], v[152:155], v[228:231], v[64:67]
	v_mfma_f32_16x16x32_bf16 v[60:63], v[156:159], v[160:163], v[60:63]
	v_mfma_f32_16x16x32_bf16 v[56:59], v[156:159], v[164:167], v[56:59]
	v_mfma_f32_16x16x32_bf16 v[52:55], v[156:159], v[224:227], v[52:55]
	v_mfma_f32_16x16x32_bf16 v[48:51], v[156:159], v[228:231], v[48:51]
	s_waitcnt lgkmcnt(0)
	v_mfma_f32_16x16x32_bf16 v[108:111], v[112:115], v[128:131], v[108:111]
	ds_read_b128 v[144:147], v216 offset:32768
	v_mfma_f32_16x16x32_bf16 v[104:107], v[112:115], v[132:135], v[104:107]
	ds_read_b128 v[148:151], v216 offset:34816
	v_mfma_f32_16x16x32_bf16 v[100:103], v[112:115], v[136:139], v[100:103]
	ds_read_b128 v[152:155], v216 offset:36864
	v_mfma_f32_16x16x32_bf16 v[96:99], v[112:115], v[140:143], v[96:99]
	ds_read_b128 v[156:159], v216 offset:38912
	v_mfma_f32_16x16x32_bf16 v[92:95], v[116:119], v[128:131], v[92:95]
	ds_read_b128 v[160:163], v220
	v_mfma_f32_16x16x32_bf16 v[88:91], v[116:119], v[132:135], v[88:91]
	ds_read_b128 v[164:167], v220 offset:2048
	v_mfma_f32_16x16x32_bf16 v[84:87], v[116:119], v[136:139], v[84:87]
	ds_read_b128 v[224:227], v220 offset:4096
	v_mfma_f32_16x16x32_bf16 v[80:83], v[116:119], v[140:143], v[80:83]
	ds_read_b128 v[228:231], v220 offset:6144
	v_mfma_f32_16x16x32_bf16 v[76:79], v[120:123], v[128:131], v[76:79]
	v_mfma_f32_16x16x32_bf16 v[72:75], v[120:123], v[132:135], v[72:75]
	v_mfma_f32_16x16x32_bf16 v[68:71], v[120:123], v[136:139], v[68:71]
	v_mfma_f32_16x16x32_bf16 v[64:67], v[120:123], v[140:143], v[64:67]
	v_mfma_f32_16x16x32_bf16 v[60:63], v[124:127], v[128:131], v[60:63]
	v_mfma_f32_16x16x32_bf16 v[56:59], v[124:127], v[132:135], v[56:59]
	v_mfma_f32_16x16x32_bf16 v[52:55], v[124:127], v[136:139], v[52:55]
	v_mfma_f32_16x16x32_bf16 v[48:51], v[124:127], v[140:143], v[48:51]
	s_add_i32 s19, s19, 2
	s_add_u32 s100, s100, 0x100
	s_addc_u32 s101, s101, 0
	s_add_u32 s98, s98, 0x100
	s_addc_u32 s99, s99, 0
	s_waitcnt lgkmcnt(0)
	v_mfma_f32_16x16x32_bf16 v[108:111], v[144:147], v[160:163], v[108:111]
	v_mfma_f32_16x16x32_bf16 v[104:107], v[144:147], v[164:167], v[104:107]
	v_mfma_f32_16x16x32_bf16 v[100:103], v[144:147], v[224:227], v[100:103]
	v_mfma_f32_16x16x32_bf16 v[96:99], v[144:147], v[228:231], v[96:99]
	v_mfma_f32_16x16x32_bf16 v[92:95], v[148:151], v[160:163], v[92:95]
	v_mfma_f32_16x16x32_bf16 v[88:91], v[148:151], v[164:167], v[88:91]
	v_mfma_f32_16x16x32_bf16 v[84:87], v[148:151], v[224:227], v[84:87]
	v_mfma_f32_16x16x32_bf16 v[80:83], v[148:151], v[228:231], v[80:83]
	v_mfma_f32_16x16x32_bf16 v[76:79], v[152:155], v[160:163], v[76:79]
	v_mfma_f32_16x16x32_bf16 v[72:75], v[152:155], v[164:167], v[72:75]
	v_mfma_f32_16x16x32_bf16 v[68:71], v[152:155], v[224:227], v[68:71]
	v_mfma_f32_16x16x32_bf16 v[64:67], v[152:155], v[228:231], v[64:67]
	v_mfma_f32_16x16x32_bf16 v[60:63], v[156:159], v[160:163], v[60:63]
	v_mfma_f32_16x16x32_bf16 v[56:59], v[156:159], v[164:167], v[56:59]
	v_mfma_f32_16x16x32_bf16 v[52:55], v[156:159], v[224:227], v[52:55]
	v_mfma_f32_16x16x32_bf16 v[48:51], v[156:159], v[228:231], v[48:51]
	s_and_b64 vcc, exec, s[10:11]
	s_nop 7
	s_branch .LBB0_1559
